# GEMM k-loops design F: full-128B-row global loads (natural lane order), slab staged into 3-stage LDS ring with fills and prefetch spread over the odd slice, fragment reads one slice ahead
# speedup vs baseline: 1.0695x; 1.0487x over previous
; __device__ __forceinline__ int otid() { int t = threadIdx.x; asm volatile("" : "+v"(t)); return t; }
; template <int MODE>
; __device__ void gemm_tile2(const u16* __restrict__ X, int lda, const u16* __restrict__ W, int ldb, int K,
;                            int m0, int n0, u16* __restrict__ outb, int vbase,
;                            const float* resid, float* outf, unsigned char* smem) {
;     ...
;   const int tid = otid(), lane = tid & 63, l15 = lane & 15, quad = lane >> 4;
;   const int wave = tid >> 6;
;   const int wx = wave >> 1, ww = wave & 1;
;   f32x4 acc[8][4];
; #pragma unroll
;   for (int i = 0; i < 8; ++i)
; #pragma unroll
;     for (int j = 0; j < 4; ++j) acc[i][j] = f32x4{0.f, 0.f, 0.f, 0.f};
;   u32x4 rx[2][4], rw[2][2];
;   const int lrow = tid >> 2, lkc = (tid & 3) * 8;
;   const int lsw = ((tid & 3) ^ ((0 - (lrow >> 2)) & 3)) * 8;
;   const int fsw = (quad ^ ((0 - (l15 >> 2)) & 3)) * 8;
;   const auto rsX = __builtin_amdgcn_make_buffer_rsrc((void*)(X + (size_t)m0 * lda), (short)0, 0x7fffffff, 0x00020000);
;   const auto rsW = __builtin_amdgcn_make_buffer_rsrc((void*)(W + (size_t)n0 * ldb), (short)0, 0x7fffffff, 0x00020000);
;   const int vox = (lrow * lda + lkc) * 2, vow = (lrow * ldb + lkc) * 2;
;   const int nk = K / 32;
;     ...
;   G2_GLOAD(0, 0);
;   G2_GLOAD(1, 1);
;   __syncthreads();
;   G2_LSTORE(0, 0);
;   G2_GLOAD(0, 2);
;   __syncthreads();
.LBB0_312:
	v_mov_b32_e32 v0, v210
	s_lshl_b32 s0, s31, 7
	s_lshl_b32 s6, s18, 19
	s_add_u32 s24, s36, s6
	s_addc_u32 s6, s37, 0
	s_and_b32 s25, s6, 0xffff
	s_lshl_b32 s6, s31, 18
	s_add_u32 s40, s8, s6
	s_addc_u32 s6, s9, 0
	s_and_b32 s41, s6, 0xffff
	s_mov_b32 s42, s26
	s_mov_b32 s43, s27
	v_lshlrev_b32_e32 v230, 4, v0
	v_lshrrev_b32_e32 v231, 4, v0
	v_bfe_u32 v233, v0, 6, 1
	v_lshrrev_b32_e32 v2, 2, v0
	v_sub_u32_e32 v2, 0, v2
	v_lshrrev_b32_e32 v3, 4, v0
	v_xor_b32_e32 v2, v3, v2
	v_lshlrev_b32_e32 v2, 4, v2
	v_and_b32_e32 v2, 48, v2
	v_lshlrev_b32_e32 v4, 6, v0
	v_and_b32_e32 v5, 0x3c0, v4
	v_bfe_u32 v6, v0, 6, 1
	v_lshl_or_b32 v6, v6, 12, v2
	v_add_u32_e32 v235, v6, v5
	v_and_b32_e32 v4, 0xffffe3c0, v4
	v_add_u32_e32 v236, v2, v4
	v_xor_b32_e32 v232, 64, v235
	v_add_u32_e32 v232, 0x6000, v232
	v_xor_b32_e32 v237, 64, v236
	v_add_u32_e32 v237, 0x6000, v237
	v_and_b32_e32 v2, 3, v0
	v_bfe_u32 v221, v0, 2, 1
	v_lshrrev_b32_e32 v4, 3, v0
	v_lshrrev_b32_e32 v5, 2, v4
	v_sub_u32_e32 v5, 0, v5
	v_and_b32_e32 v5, 3, v5
	v_xor_b32_e32 v5, v2, v5
	v_lshlrev_b32_e32 v5, 4, v5
	v_lshl_or_b32 v5, v221, 6, v5
	v_lshl_or_b32 v218, v4, 11, v5
	v_add_u32_e32 v219, 0x10000, v218
	v_lshlrev_b32_e32 v2, 4, v2
	v_xor_b32_e32 v4, v4, v221
	v_lshl_or_b32 v220, v4, 6, v2
	buffer_load_dwordx4 v[2:5], v218, s[24:27], 0 offen
	buffer_load_dwordx4 v[6:9], v219, s[24:27], 0 offen
	buffer_load_dwordx4 v[10:13], v218, s[24:27], s27 offen
	buffer_load_dwordx4 v[14:17], v219, s[24:27], s27 offen
	buffer_load_dwordx4 v[18:21], v218, s[24:27], s77 offen
	buffer_load_dwordx4 v[22:25], v219, s[24:27], s77 offen
	buffer_load_dwordx4 v[26:29], v218, s[24:27], s78 offen
	buffer_load_dwordx4 v[30:33], v219, s[24:27], s78 offen
	buffer_load_dwordx4 v[34:37], v218, s[40:43], 0 offen
	buffer_load_dwordx4 v[38:41], v219, s[40:43], 0 offen
	buffer_load_dwordx4 v[42:45], v218, s[40:43], s27 offen
	buffer_load_dwordx4 v[46:49], v219, s[40:43], s27 offen
	v_add_u32_e32 v218, 0x80, v218
	v_add_u32_e32 v219, 0x80, v219
	v_mov_b32_e32 v50, 0
	v_mov_b32_e32 v51, 0
	v_mov_b32_e32 v52, 0
	v_mov_b32_e32 v53, 0
	v_mov_b32_e32 v54, 0
	v_mov_b32_e32 v55, 0
	v_mov_b32_e32 v56, 0
	v_mov_b32_e32 v57, 0
	v_mov_b32_e32 v58, 0
	v_mov_b32_e32 v59, 0
	v_mov_b32_e32 v60, 0
	v_mov_b32_e32 v61, 0
	v_mov_b32_e32 v62, 0
	v_mov_b32_e32 v63, 0
	v_mov_b32_e32 v64, 0
	v_mov_b32_e32 v65, 0
	v_mov_b32_e32 v66, 0
	v_mov_b32_e32 v67, 0
	v_mov_b32_e32 v68, 0
	v_mov_b32_e32 v69, 0
	v_mov_b32_e32 v70, 0
	v_mov_b32_e32 v71, 0
	v_mov_b32_e32 v72, 0
	v_mov_b32_e32 v73, 0
	v_mov_b32_e32 v74, 0
	v_mov_b32_e32 v75, 0
	v_mov_b32_e32 v76, 0
	v_mov_b32_e32 v77, 0
	v_mov_b32_e32 v78, 0
	v_mov_b32_e32 v79, 0
	v_mov_b32_e32 v80, 0
	v_mov_b32_e32 v81, 0
	v_mov_b32_e32 v82, 0
	v_mov_b32_e32 v83, 0
	v_mov_b32_e32 v84, 0
	v_mov_b32_e32 v85, 0
	v_mov_b32_e32 v86, 0
	v_mov_b32_e32 v87, 0
	v_mov_b32_e32 v88, 0
	v_mov_b32_e32 v89, 0
	v_mov_b32_e32 v90, 0
	v_mov_b32_e32 v91, 0
	v_mov_b32_e32 v92, 0
	v_mov_b32_e32 v93, 0
	v_mov_b32_e32 v94, 0
	v_mov_b32_e32 v95, 0
	v_mov_b32_e32 v96, 0
	v_mov_b32_e32 v97, 0
	v_mov_b32_e32 v98, 0
	v_mov_b32_e32 v99, 0
	v_mov_b32_e32 v100, 0
	v_mov_b32_e32 v101, 0
	v_mov_b32_e32 v102, 0
	v_mov_b32_e32 v103, 0
	v_mov_b32_e32 v104, 0
	v_mov_b32_e32 v105, 0
	v_mov_b32_e32 v106, 0
	v_mov_b32_e32 v107, 0
	v_mov_b32_e32 v108, 0
	v_mov_b32_e32 v109, 0
	v_mov_b32_e32 v110, 0
	v_mov_b32_e32 v111, 0
	v_mov_b32_e32 v112, 0
	v_mov_b32_e32 v113, 0
	v_mov_b32_e32 v114, 0
	v_mov_b32_e32 v115, 0
	v_mov_b32_e32 v116, 0
	v_mov_b32_e32 v117, 0
	v_mov_b32_e32 v118, 0
	v_mov_b32_e32 v119, 0
	v_mov_b32_e32 v120, 0
	v_mov_b32_e32 v121, 0
	v_mov_b32_e32 v122, 0
	v_mov_b32_e32 v123, 0
	v_mov_b32_e32 v124, 0
	v_mov_b32_e32 v125, 0
	v_mov_b32_e32 v126, 0
	v_mov_b32_e32 v127, 0
	v_mov_b32_e32 v128, 0
	v_mov_b32_e32 v129, 0
	v_mov_b32_e32 v130, 0
	v_mov_b32_e32 v131, 0
	v_mov_b32_e32 v132, 0
	v_mov_b32_e32 v133, 0
	v_mov_b32_e32 v134, 0
	v_mov_b32_e32 v135, 0
	v_mov_b32_e32 v136, 0
	v_mov_b32_e32 v137, 0
	v_mov_b32_e32 v138, 0
	v_mov_b32_e32 v139, 0
	v_mov_b32_e32 v140, 0
	v_mov_b32_e32 v141, 0
	v_mov_b32_e32 v142, 0
	v_mov_b32_e32 v143, 0
	v_mov_b32_e32 v144, 0
	v_mov_b32_e32 v145, 0
	v_mov_b32_e32 v146, 0
	v_mov_b32_e32 v147, 0
	v_mov_b32_e32 v148, 0
	v_mov_b32_e32 v149, 0
	v_mov_b32_e32 v150, 0
	v_mov_b32_e32 v151, 0
	v_mov_b32_e32 v152, 0
	v_mov_b32_e32 v153, 0
	v_mov_b32_e32 v154, 0
	v_mov_b32_e32 v155, 0
	v_mov_b32_e32 v156, 0
	v_mov_b32_e32 v157, 0
	v_mov_b32_e32 v158, 0
	v_mov_b32_e32 v159, 0
	v_mov_b32_e32 v160, 0
	v_mov_b32_e32 v161, 0
	v_mov_b32_e32 v162, 0
	v_mov_b32_e32 v163, 0
	v_mov_b32_e32 v164, 0
	v_mov_b32_e32 v165, 0
	v_mov_b32_e32 v166, 0
	v_mov_b32_e32 v167, 0
	v_mov_b32_e32 v168, 0
	v_mov_b32_e32 v169, 0
	v_mov_b32_e32 v170, 0
	v_mov_b32_e32 v171, 0
	v_mov_b32_e32 v172, 0
	v_mov_b32_e32 v173, 0
	v_mov_b32_e32 v174, 0
	v_mov_b32_e32 v175, 0
	v_mov_b32_e32 v176, 0
	v_mov_b32_e32 v177, 0
	s_mov_b32 s6, 0
	s_mov_b32 s7, 0x6000
	s_mov_b32 s35, 0xc000
	s_mov_b32 s1, 0
	v_mad_i32_i24 v234, v221, s7, v220
	s_barrier
	s_waitcnt vmcnt(11)
	ds_write_b128 v234, v[2:5]
	s_waitcnt vmcnt(10)
	ds_write_b128 v234, v[6:9] offset:2048
	s_waitcnt vmcnt(9)
	ds_write_b128 v234, v[10:13] offset:4096
	s_waitcnt vmcnt(8)
	ds_write_b128 v234, v[14:17] offset:6144
	s_waitcnt vmcnt(7)
	ds_write_b128 v234, v[18:21] offset:8192
	s_waitcnt vmcnt(6)
	ds_write_b128 v234, v[22:25] offset:10240
	s_waitcnt vmcnt(5)
	ds_write_b128 v234, v[26:29] offset:12288
	s_waitcnt vmcnt(4)
	ds_write_b128 v234, v[30:33] offset:14336
	s_waitcnt vmcnt(3)
	ds_write_b128 v234, v[34:37] offset:16384
	s_waitcnt vmcnt(2)
	ds_write_b128 v234, v[38:41] offset:18432
	s_waitcnt vmcnt(1)
	ds_write_b128 v234, v[42:45] offset:20480
	s_waitcnt vmcnt(0)
	ds_write_b128 v234, v[46:49] offset:22528
	buffer_load_dwordx4 v[2:5], v218, s[24:27], 0 offen
	buffer_load_dwordx4 v[6:9], v219, s[24:27], 0 offen
	buffer_load_dwordx4 v[10:13], v218, s[24:27], s27 offen
	buffer_load_dwordx4 v[14:17], v219, s[24:27], s27 offen
	buffer_load_dwordx4 v[18:21], v218, s[24:27], s77 offen
	buffer_load_dwordx4 v[22:25], v219, s[24:27], s77 offen
	buffer_load_dwordx4 v[26:29], v218, s[24:27], s78 offen
	buffer_load_dwordx4 v[30:33], v219, s[24:27], s78 offen
	buffer_load_dwordx4 v[34:37], v218, s[40:43], 0 offen
	buffer_load_dwordx4 v[38:41], v219, s[40:43], 0 offen
	buffer_load_dwordx4 v[42:45], v218, s[40:43], s27 offen
	buffer_load_dwordx4 v[46:49], v219, s[40:43], s27 offen
	v_add_u32_e32 v218, 0x80, v218
	v_add_u32_e32 v219, 0x80, v219
	s_waitcnt lgkmcnt(0)
	s_barrier
	ds_read_b128 v[178:181], v235 offset:16384
	ds_read_b128 v[182:185], v235 offset:17408
	ds_read_b128 v[186:189], v235 offset:18432
	ds_read_b128 v[190:193], v235 offset:19456
	ds_read_b128 v[194:197], v236
	ds_read_b128 v[198:201], v236 offset:1024
	ds_read_b128 v[202:205], v236 offset:2048
	ds_read_b128 v[206:209], v236 offset:3072
; template <int MODE>
; __device__ void gemm_tile2(const u16* __restrict__ X, int lda, const u16* __restrict__ W, int ldb, int K,
;                            int m0, int n0, u16* __restrict__ outb, int vbase,
;                            const float* resid, float* outf, unsigned char* smem) {
;     ...
;   for (int kt2 = 0; kt2 < nk; kt2 += 2) {
; #pragma unroll
;     for (int h = 0; h < 2; ++h) {
;       const int kt = kt2 + h;
;       const u16* st = sbase + h * G2STAGE;
;       bf16x8 fw[4], fx[4];
; #pragma unroll
;       for (int j = 0; j < 4; ++j) fw[j] = *(const bf16x8*)(st + 256 * G2S + (ww * 64 + j * 16 + l15) * G2S + fsw);
; #pragma unroll
;       for (int i = 0; i < 4; ++i) fx[i] = *(const bf16x8*)(st + (wx * 128 + i * 16 + l15) * G2S + fsw);
;       __builtin_amdgcn_sched_barrier(0);
;       __builtin_amdgcn_s_setprio(1);
; #pragma unroll
;       for (int i = 0; i < 4; ++i) {
; #pragma unroll
;         for (int j = 0; j < 4; ++j) {
;           if (MODE == 1) acc[i][j] = mfma16(fx[i], fw[j], acc[i][j]);
;           else acc[i][j] = mfma16(fw[j], fx[i], acc[i][j]);
;         }
;       }
;       __builtin_amdgcn_s_setprio(0);
;       __builtin_amdgcn_sched_barrier(0);
; #pragma unroll
;       for (int i = 0; i < 4; ++i) fx[i] = *(const bf16x8*)(st + (wx * 128 + (i + 4) * 16 + l15) * G2S + fsw);
;       __builtin_amdgcn_sched_barrier(0);
;       if (kt + 1 < nk) G2_LSTORE(1 - h, 1 - h);
;       if (kt + 3 < nk) G2_GLOAD(1 - h, kt + 3);
;       __builtin_amdgcn_sched_barrier(0);
;       __builtin_amdgcn_s_setprio(1);
; #pragma unroll
;       for (int i = 0; i < 4; ++i) {
; #pragma unroll
;         for (int j = 0; j < 4; ++j) {
;           if (MODE == 1) acc[i + 4][j] = mfma16(fx[i], fw[j], acc[i + 4][j]);
;           else acc[i + 4][j] = mfma16(fw[j], fx[i], acc[i + 4][j]);
;         }
;       }
;       __builtin_amdgcn_s_setprio(0);
;       __syncthreads();
;     }
;   }
.Lf0_loop:
	s_waitcnt lgkmcnt(3)
	v_mfma_f32_16x16x32_bf16 v[174:177], v[178:181], v[194:197], v[174:177]
	v_mfma_f32_16x16x32_bf16 v[170:173], v[182:185], v[194:197], v[170:173]
	v_mfma_f32_16x16x32_bf16 v[166:169], v[186:189], v[194:197], v[166:169]
	v_mfma_f32_16x16x32_bf16 v[162:165], v[190:193], v[194:197], v[162:165]
	ds_read_b128 v[194:197], v236 offset:4096
	ds_read_b128 v[238:241], v232 offset:16384
	s_waitcnt lgkmcnt(4)
	v_mfma_f32_16x16x32_bf16 v[158:161], v[178:181], v[198:201], v[158:161]
	v_mfma_f32_16x16x32_bf16 v[154:157], v[182:185], v[198:201], v[154:157]
	v_mfma_f32_16x16x32_bf16 v[150:153], v[186:189], v[198:201], v[150:153]
	v_mfma_f32_16x16x32_bf16 v[146:149], v[190:193], v[198:201], v[146:149]
	ds_read_b128 v[198:201], v236 offset:5120
	ds_read_b128 v[242:245], v232 offset:17408
	s_waitcnt lgkmcnt(5)
	v_mfma_f32_16x16x32_bf16 v[142:145], v[178:181], v[202:205], v[142:145]
	v_mfma_f32_16x16x32_bf16 v[138:141], v[182:185], v[202:205], v[138:141]
	v_mfma_f32_16x16x32_bf16 v[134:137], v[186:189], v[202:205], v[134:137]
	v_mfma_f32_16x16x32_bf16 v[130:133], v[190:193], v[202:205], v[130:133]
	ds_read_b128 v[202:205], v236 offset:6144
	ds_read_b128 v[246:249], v232 offset:18432
	s_waitcnt lgkmcnt(6)
	v_mfma_f32_16x16x32_bf16 v[126:129], v[178:181], v[206:209], v[126:129]
	v_mfma_f32_16x16x32_bf16 v[122:125], v[182:185], v[206:209], v[122:125]
	v_mfma_f32_16x16x32_bf16 v[118:121], v[186:189], v[206:209], v[118:121]
	v_mfma_f32_16x16x32_bf16 v[114:117], v[190:193], v[206:209], v[114:117]
	ds_read_b128 v[206:209], v236 offset:7168
	ds_read_b128 v[222:225], v232 offset:19456
	s_sub_i32 s38, s35, s6
	v_add_u32_e32 v235, s38, v235
	v_add_u32_e32 v236, s38, v236
	s_waitcnt lgkmcnt(7)
	v_mfma_f32_16x16x32_bf16 v[110:113], v[178:181], v[194:197], v[110:113]
	v_mfma_f32_16x16x32_bf16 v[106:109], v[182:185], v[194:197], v[106:109]
	v_mfma_f32_16x16x32_bf16 v[102:105], v[186:189], v[194:197], v[102:105]
	v_mfma_f32_16x16x32_bf16 v[98:101], v[190:193], v[194:197], v[98:101]
	ds_read_b128 v[194:197], v237
	s_waitcnt lgkmcnt(6)
	v_mfma_f32_16x16x32_bf16 v[94:97], v[178:181], v[198:201], v[94:97]
	v_mfma_f32_16x16x32_bf16 v[90:93], v[182:185], v[198:201], v[90:93]
	v_mfma_f32_16x16x32_bf16 v[86:89], v[186:189], v[198:201], v[86:89]
	v_mfma_f32_16x16x32_bf16 v[82:85], v[190:193], v[198:201], v[82:85]
	ds_read_b128 v[198:201], v237 offset:1024
	s_waitcnt lgkmcnt(5)
	v_mfma_f32_16x16x32_bf16 v[78:81], v[178:181], v[202:205], v[78:81]
	v_mfma_f32_16x16x32_bf16 v[74:77], v[182:185], v[202:205], v[74:77]
	v_mfma_f32_16x16x32_bf16 v[70:73], v[186:189], v[202:205], v[70:73]
	v_mfma_f32_16x16x32_bf16 v[66:69], v[190:193], v[202:205], v[66:69]
	ds_read_b128 v[202:205], v237 offset:2048
	s_waitcnt lgkmcnt(4)
	v_mfma_f32_16x16x32_bf16 v[62:65], v[178:181], v[206:209], v[62:65]
	v_mfma_f32_16x16x32_bf16 v[58:61], v[182:185], v[206:209], v[58:61]
	v_mfma_f32_16x16x32_bf16 v[54:57], v[186:189], v[206:209], v[54:57]
	v_mfma_f32_16x16x32_bf16 v[50:53], v[190:193], v[206:209], v[50:53]
	ds_read_b128 v[206:209], v237 offset:3072
	s_sub_i32 s38, s6, s35
	v_mad_i32_i24 v234, v221, s38, v220
	v_add_u32_e32 v234, s35, v234
	s_barrier
	s_waitcnt lgkmcnt(3)
	v_mfma_f32_16x16x32_bf16 v[174:177], v[238:241], v[194:197], v[174:177]
	v_mfma_f32_16x16x32_bf16 v[170:173], v[242:245], v[194:197], v[170:173]
	v_mfma_f32_16x16x32_bf16 v[166:169], v[246:249], v[194:197], v[166:169]
	v_mfma_f32_16x16x32_bf16 v[162:165], v[222:225], v[194:197], v[162:165]
	ds_read_b128 v[194:197], v237 offset:4096
	s_waitcnt vmcnt(11)
	ds_write_b128 v234, v[2:5]
	s_waitcnt vmcnt(10)
	ds_write_b128 v234, v[6:9] offset:2048
	buffer_load_dwordx4 v[2:5], v218, s[24:27], 0 offen
	buffer_load_dwordx4 v[6:9], v219, s[24:27], 0 offen
	s_waitcnt lgkmcnt(5)
	v_mfma_f32_16x16x32_bf16 v[158:161], v[238:241], v[198:201], v[158:161]
	v_mfma_f32_16x16x32_bf16 v[154:157], v[242:245], v[198:201], v[154:157]
	v_mfma_f32_16x16x32_bf16 v[150:153], v[246:249], v[198:201], v[150:153]
	v_mfma_f32_16x16x32_bf16 v[146:149], v[222:225], v[198:201], v[146:149]
	ds_read_b128 v[198:201], v237 offset:5120
	s_waitcnt vmcnt(11)
	ds_write_b128 v234, v[10:13] offset:4096
	s_waitcnt vmcnt(10)
	ds_write_b128 v234, v[14:17] offset:6144
	buffer_load_dwordx4 v[10:13], v218, s[24:27], s27 offen
	buffer_load_dwordx4 v[14:17], v219, s[24:27], s27 offen
	s_waitcnt lgkmcnt(7)
	v_mfma_f32_16x16x32_bf16 v[142:145], v[238:241], v[202:205], v[142:145]
	v_mfma_f32_16x16x32_bf16 v[138:141], v[242:245], v[202:205], v[138:141]
	v_mfma_f32_16x16x32_bf16 v[134:137], v[246:249], v[202:205], v[134:137]
	v_mfma_f32_16x16x32_bf16 v[130:133], v[222:225], v[202:205], v[130:133]
	ds_read_b128 v[202:205], v237 offset:6144
	s_waitcnt vmcnt(11)
	ds_write_b128 v234, v[18:21] offset:8192
	s_waitcnt vmcnt(10)
	ds_write_b128 v234, v[22:25] offset:10240
	buffer_load_dwordx4 v[18:21], v218, s[24:27], s77 offen
	buffer_load_dwordx4 v[22:25], v219, s[24:27], s77 offen
	s_waitcnt lgkmcnt(9)
	v_mfma_f32_16x16x32_bf16 v[126:129], v[238:241], v[206:209], v[126:129]
	v_mfma_f32_16x16x32_bf16 v[122:125], v[242:245], v[206:209], v[122:125]
	v_mfma_f32_16x16x32_bf16 v[118:121], v[246:249], v[206:209], v[118:121]
	v_mfma_f32_16x16x32_bf16 v[114:117], v[222:225], v[206:209], v[114:117]
	ds_read_b128 v[206:209], v237 offset:7168
	s_sub_i32 s38, s6, s7
	v_add_u32_e32 v232, s38, v232
	v_add_u32_e32 v237, s38, v237
	s_waitcnt vmcnt(11)
	ds_write_b128 v234, v[26:29] offset:12288
	s_waitcnt vmcnt(10)
	ds_write_b128 v234, v[30:33] offset:14336
	buffer_load_dwordx4 v[26:29], v218, s[24:27], s78 offen
	buffer_load_dwordx4 v[30:33], v219, s[24:27], s78 offen
	s_waitcnt lgkmcnt(11)
; template <int MODE>
; __device__ void gemm_tile2(const u16* __restrict__ X, int lda, const u16* __restrict__ W, int ldb, int K,
;                            int m0, int n0, u16* __restrict__ outb, int vbase,
;                            const float* resid, float* outf, unsigned char* smem) {
;     ...
;   for (int kt2 = 0; kt2 < nk; kt2 += 2) {
; #pragma unroll
;     for (int h = 0; h < 2; ++h) {
;       const int kt = kt2 + h;
;       const u16* st = sbase + h * G2STAGE;
;       bf16x8 fw[4], fx[4];
; #pragma unroll
;       for (int j = 0; j < 4; ++j) fw[j] = *(const bf16x8*)(st + 256 * G2S + (ww * 64 + j * 16 + l15) * G2S + fsw);
; #pragma unroll
;       for (int i = 0; i < 4; ++i) fx[i] = *(const bf16x8*)(st + (wx * 128 + i * 16 + l15) * G2S + fsw);
;       __builtin_amdgcn_sched_barrier(0);
;       __builtin_amdgcn_s_setprio(1);
; #pragma unroll
;       for (int i = 0; i < 4; ++i) {
; #pragma unroll
;         for (int j = 0; j < 4; ++j) {
;           if (MODE == 1) acc[i][j] = mfma16(fx[i], fw[j], acc[i][j]);
;           else acc[i][j] = mfma16(fw[j], fx[i], acc[i][j]);
;         }
;       }
;       __builtin_amdgcn_s_setprio(0);
;       __builtin_amdgcn_sched_barrier(0);
; #pragma unroll
;       for (int i = 0; i < 4; ++i) fx[i] = *(const bf16x8*)(st + (wx * 128 + (i + 4) * 16 + l15) * G2S + fsw);
;       __builtin_amdgcn_sched_barrier(0);
;       if (kt + 1 < nk) G2_LSTORE(1 - h, 1 - h);
;       if (kt + 3 < nk) G2_GLOAD(1 - h, kt + 3);
;       __builtin_amdgcn_sched_barrier(0);
;       __builtin_amdgcn_s_setprio(1);
; #pragma unroll
;       for (int i = 0; i < 4; ++i) {
; #pragma unroll
;         for (int j = 0; j < 4; ++j) {
;           if (MODE == 1) acc[i + 4][j] = mfma16(fx[i], fw[j], acc[i + 4][j]);
;           else acc[i + 4][j] = mfma16(fw[j], fx[i], acc[i + 4][j]);
;         }
;       }
;       __builtin_amdgcn_s_setprio(0);
;       __syncthreads();
;     }
;   }
	v_mfma_f32_16x16x32_bf16 v[110:113], v[238:241], v[194:197], v[110:113]
	v_mfma_f32_16x16x32_bf16 v[106:109], v[242:245], v[194:197], v[106:109]
	v_mfma_f32_16x16x32_bf16 v[102:105], v[246:249], v[194:197], v[102:105]
	v_mfma_f32_16x16x32_bf16 v[98:101], v[222:225], v[194:197], v[98:101]
	s_waitcnt vmcnt(11)
	ds_write_b128 v234, v[34:37] offset:16384
	s_waitcnt vmcnt(10)
	ds_write_b128 v234, v[38:41] offset:18432
	buffer_load_dwordx4 v[34:37], v218, s[40:43], 0 offen
	buffer_load_dwordx4 v[38:41], v219, s[40:43], 0 offen
	s_waitcnt lgkmcnt(10)
	v_mfma_f32_16x16x32_bf16 v[94:97], v[238:241], v[198:201], v[94:97]
	v_mfma_f32_16x16x32_bf16 v[90:93], v[242:245], v[198:201], v[90:93]
	v_mfma_f32_16x16x32_bf16 v[86:89], v[246:249], v[198:201], v[86:89]
	v_mfma_f32_16x16x32_bf16 v[82:85], v[222:225], v[198:201], v[82:85]
	s_waitcnt vmcnt(11)
	ds_write_b128 v234, v[42:45] offset:20480
	s_waitcnt vmcnt(10)
	ds_write_b128 v234, v[46:49] offset:22528
	buffer_load_dwordx4 v[42:45], v218, s[40:43], s27 offen
	buffer_load_dwordx4 v[46:49], v219, s[40:43], s27 offen
	s_waitcnt lgkmcnt(9)
	v_mfma_f32_16x16x32_bf16 v[78:81], v[238:241], v[202:205], v[78:81]
	v_mfma_f32_16x16x32_bf16 v[74:77], v[242:245], v[202:205], v[74:77]
	v_mfma_f32_16x16x32_bf16 v[70:73], v[246:249], v[202:205], v[70:73]
	v_mfma_f32_16x16x32_bf16 v[66:69], v[222:225], v[202:205], v[66:69]
	s_waitcnt lgkmcnt(6)
	v_mfma_f32_16x16x32_bf16 v[62:65], v[238:241], v[206:209], v[62:65]
	v_mfma_f32_16x16x32_bf16 v[58:61], v[242:245], v[206:209], v[58:61]
	v_mfma_f32_16x16x32_bf16 v[54:57], v[246:249], v[206:209], v[54:57]
	v_mfma_f32_16x16x32_bf16 v[50:53], v[222:225], v[206:209], v[50:53]
	v_add_u32_e32 v218, 0x80, v218
	v_add_u32_e32 v219, 0x80, v219
	s_waitcnt lgkmcnt(0)
	s_barrier
	s_mov_b32 s38, s35
	s_mov_b32 s35, s7
	s_mov_b32 s7, s6
	s_mov_b32 s6, s38
	ds_read_b128 v[178:181], v235 offset:16384
	ds_read_b128 v[182:185], v235 offset:17408
	ds_read_b128 v[186:189], v235 offset:18432
	ds_read_b128 v[190:193], v235 offset:19456
	ds_read_b128 v[194:197], v236
	ds_read_b128 v[198:201], v236 offset:1024
	ds_read_b128 v[202:205], v236 offset:2048
	ds_read_b128 v[206:209], v236 offset:3072
	s_add_u32 s1, s1, 1
	s_cmp_lt_u32 s1, 14
	s_cbranch_scc1 .Lf0_loop
	s_waitcnt lgkmcnt(3)
	v_mfma_f32_16x16x32_bf16 v[174:177], v[178:181], v[194:197], v[174:177]
	v_mfma_f32_16x16x32_bf16 v[170:173], v[182:185], v[194:197], v[170:173]
	v_mfma_f32_16x16x32_bf16 v[166:169], v[186:189], v[194:197], v[166:169]
	v_mfma_f32_16x16x32_bf16 v[162:165], v[190:193], v[194:197], v[162:165]
	ds_read_b128 v[194:197], v236 offset:4096
	ds_read_b128 v[238:241], v232 offset:16384
	s_waitcnt lgkmcnt(4)
	v_mfma_f32_16x16x32_bf16 v[158:161], v[178:181], v[198:201], v[158:161]
	v_mfma_f32_16x16x32_bf16 v[154:157], v[182:185], v[198:201], v[154:157]
	v_mfma_f32_16x16x32_bf16 v[150:153], v[186:189], v[198:201], v[150:153]
	v_mfma_f32_16x16x32_bf16 v[146:149], v[190:193], v[198:201], v[146:149]
	ds_read_b128 v[198:201], v236 offset:5120
	ds_read_b128 v[242:245], v232 offset:17408
	s_waitcnt lgkmcnt(5)
	v_mfma_f32_16x16x32_bf16 v[142:145], v[178:181], v[202:205], v[142:145]
	v_mfma_f32_16x16x32_bf16 v[138:141], v[182:185], v[202:205], v[138:141]
	v_mfma_f32_16x16x32_bf16 v[134:137], v[186:189], v[202:205], v[134:137]
	v_mfma_f32_16x16x32_bf16 v[130:133], v[190:193], v[202:205], v[130:133]
	ds_read_b128 v[202:205], v236 offset:6144
	ds_read_b128 v[246:249], v232 offset:18432
	s_waitcnt lgkmcnt(6)
	v_mfma_f32_16x16x32_bf16 v[126:129], v[178:181], v[206:209], v[126:129]
	v_mfma_f32_16x16x32_bf16 v[122:125], v[182:185], v[206:209], v[122:125]
	v_mfma_f32_16x16x32_bf16 v[118:121], v[186:189], v[206:209], v[118:121]
	v_mfma_f32_16x16x32_bf16 v[114:117], v[190:193], v[206:209], v[114:117]
	ds_read_b128 v[206:209], v236 offset:7168
	ds_read_b128 v[222:225], v232 offset:19456
	s_sub_i32 s38, s35, s6
	v_add_u32_e32 v235, s38, v235
	v_add_u32_e32 v236, s38, v236
	s_waitcnt lgkmcnt(7)
	v_mfma_f32_16x16x32_bf16 v[110:113], v[178:181], v[194:197], v[110:113]
	v_mfma_f32_16x16x32_bf16 v[106:109], v[182:185], v[194:197], v[106:109]
	v_mfma_f32_16x16x32_bf16 v[102:105], v[186:189], v[194:197], v[102:105]
	v_mfma_f32_16x16x32_bf16 v[98:101], v[190:193], v[194:197], v[98:101]
	ds_read_b128 v[194:197], v237
	s_waitcnt lgkmcnt(6)
	v_mfma_f32_16x16x32_bf16 v[94:97], v[178:181], v[198:201], v[94:97]
	v_mfma_f32_16x16x32_bf16 v[90:93], v[182:185], v[198:201], v[90:93]
	v_mfma_f32_16x16x32_bf16 v[86:89], v[186:189], v[198:201], v[86:89]
	v_mfma_f32_16x16x32_bf16 v[82:85], v[190:193], v[198:201], v[82:85]
	ds_read_b128 v[198:201], v237 offset:1024
	s_waitcnt lgkmcnt(5)
	v_mfma_f32_16x16x32_bf16 v[78:81], v[178:181], v[202:205], v[78:81]
	v_mfma_f32_16x16x32_bf16 v[74:77], v[182:185], v[202:205], v[74:77]
	v_mfma_f32_16x16x32_bf16 v[70:73], v[186:189], v[202:205], v[70:73]
	v_mfma_f32_16x16x32_bf16 v[66:69], v[190:193], v[202:205], v[66:69]
	ds_read_b128 v[202:205], v237 offset:2048
	s_waitcnt lgkmcnt(4)
	v_mfma_f32_16x16x32_bf16 v[62:65], v[178:181], v[206:209], v[62:65]
	v_mfma_f32_16x16x32_bf16 v[58:61], v[182:185], v[206:209], v[58:61]
	v_mfma_f32_16x16x32_bf16 v[54:57], v[186:189], v[206:209], v[54:57]
	v_mfma_f32_16x16x32_bf16 v[50:53], v[190:193], v[206:209], v[50:53]
	ds_read_b128 v[206:209], v237 offset:3072
	s_sub_i32 s38, s6, s35
	v_mad_i32_i24 v234, v221, s38, v220
	v_add_u32_e32 v234, s35, v234
	s_barrier
; template <int MODE>
; __device__ void gemm_tile2(const u16* __restrict__ X, int lda, const u16* __restrict__ W, int ldb, int K,
;                            int m0, int n0, u16* __restrict__ outb, int vbase,
;                            const float* resid, float* outf, unsigned char* smem) {
;     ...
;   for (int kt2 = 0; kt2 < nk; kt2 += 2) {
; #pragma unroll
;     for (int h = 0; h < 2; ++h) {
;       const int kt = kt2 + h;
;       const u16* st = sbase + h * G2STAGE;
;       bf16x8 fw[4], fx[4];
; #pragma unroll
;       for (int j = 0; j < 4; ++j) fw[j] = *(const bf16x8*)(st + 256 * G2S + (ww * 64 + j * 16 + l15) * G2S + fsw);
; #pragma unroll
;       for (int i = 0; i < 4; ++i) fx[i] = *(const bf16x8*)(st + (wx * 128 + i * 16 + l15) * G2S + fsw);
;       __builtin_amdgcn_sched_barrier(0);
;       __builtin_amdgcn_s_setprio(1);
; #pragma unroll
;       for (int i = 0; i < 4; ++i) {
; #pragma unroll
;         for (int j = 0; j < 4; ++j) {
;           if (MODE == 1) acc[i][j] = mfma16(fx[i], fw[j], acc[i][j]);
;           else acc[i][j] = mfma16(fw[j], fx[i], acc[i][j]);
;         }
;       }
;       __builtin_amdgcn_s_setprio(0);
;       __builtin_amdgcn_sched_barrier(0);
; #pragma unroll
;       for (int i = 0; i < 4; ++i) fx[i] = *(const bf16x8*)(st + (wx * 128 + (i + 4) * 16 + l15) * G2S + fsw);
;       __builtin_amdgcn_sched_barrier(0);
;       if (kt + 1 < nk) G2_LSTORE(1 - h, 1 - h);
;       if (kt + 3 < nk) G2_GLOAD(1 - h, kt + 3);
;       __builtin_amdgcn_sched_barrier(0);
;       __builtin_amdgcn_s_setprio(1);
; #pragma unroll
;       for (int i = 0; i < 4; ++i) {
; #pragma unroll
;         for (int j = 0; j < 4; ++j) {
;           if (MODE == 1) acc[i + 4][j] = mfma16(fx[i], fw[j], acc[i + 4][j]);
;           else acc[i + 4][j] = mfma16(fw[j], fx[i], acc[i + 4][j]);
;         }
;       }
;       __builtin_amdgcn_s_setprio(0);
;       __syncthreads();
;     }
;   }
	s_waitcnt lgkmcnt(3)
	v_mfma_f32_16x16x32_bf16 v[174:177], v[238:241], v[194:197], v[174:177]
	v_mfma_f32_16x16x32_bf16 v[170:173], v[242:245], v[194:197], v[170:173]
	v_mfma_f32_16x16x32_bf16 v[166:169], v[246:249], v[194:197], v[166:169]
	v_mfma_f32_16x16x32_bf16 v[162:165], v[222:225], v[194:197], v[162:165]
	ds_read_b128 v[194:197], v237 offset:4096
	s_waitcnt vmcnt(11)
	ds_write_b128 v234, v[2:5]
	s_waitcnt vmcnt(10)
	ds_write_b128 v234, v[6:9] offset:2048
	s_waitcnt lgkmcnt(5)
	v_mfma_f32_16x16x32_bf16 v[158:161], v[238:241], v[198:201], v[158:161]
	v_mfma_f32_16x16x32_bf16 v[154:157], v[242:245], v[198:201], v[154:157]
	v_mfma_f32_16x16x32_bf16 v[150:153], v[246:249], v[198:201], v[150:153]
	v_mfma_f32_16x16x32_bf16 v[146:149], v[222:225], v[198:201], v[146:149]
	ds_read_b128 v[198:201], v237 offset:5120
	s_waitcnt vmcnt(9)
	ds_write_b128 v234, v[10:13] offset:4096
	s_waitcnt vmcnt(8)
	ds_write_b128 v234, v[14:17] offset:6144
	s_waitcnt lgkmcnt(7)
	v_mfma_f32_16x16x32_bf16 v[142:145], v[238:241], v[202:205], v[142:145]
	v_mfma_f32_16x16x32_bf16 v[138:141], v[242:245], v[202:205], v[138:141]
	v_mfma_f32_16x16x32_bf16 v[134:137], v[246:249], v[202:205], v[134:137]
	v_mfma_f32_16x16x32_bf16 v[130:133], v[222:225], v[202:205], v[130:133]
	ds_read_b128 v[202:205], v237 offset:6144
	s_waitcnt vmcnt(7)
	ds_write_b128 v234, v[18:21] offset:8192
	s_waitcnt vmcnt(6)
	ds_write_b128 v234, v[22:25] offset:10240
	s_waitcnt lgkmcnt(9)
	v_mfma_f32_16x16x32_bf16 v[126:129], v[238:241], v[206:209], v[126:129]
	v_mfma_f32_16x16x32_bf16 v[122:125], v[242:245], v[206:209], v[122:125]
	v_mfma_f32_16x16x32_bf16 v[118:121], v[246:249], v[206:209], v[118:121]
	v_mfma_f32_16x16x32_bf16 v[114:117], v[222:225], v[206:209], v[114:117]
	ds_read_b128 v[206:209], v237 offset:7168
	s_sub_i32 s38, s6, s7
	v_add_u32_e32 v232, s38, v232
	v_add_u32_e32 v237, s38, v237
	s_waitcnt vmcnt(5)
	ds_write_b128 v234, v[26:29] offset:12288
	s_waitcnt vmcnt(4)
	ds_write_b128 v234, v[30:33] offset:14336
	s_waitcnt lgkmcnt(11)
	v_mfma_f32_16x16x32_bf16 v[110:113], v[238:241], v[194:197], v[110:113]
	v_mfma_f32_16x16x32_bf16 v[106:109], v[242:245], v[194:197], v[106:109]
	v_mfma_f32_16x16x32_bf16 v[102:105], v[246:249], v[194:197], v[102:105]
	v_mfma_f32_16x16x32_bf16 v[98:101], v[222:225], v[194:197], v[98:101]
	s_waitcnt vmcnt(3)
	ds_write_b128 v234, v[34:37] offset:16384
	s_waitcnt vmcnt(2)
	ds_write_b128 v234, v[38:41] offset:18432
	s_waitcnt lgkmcnt(10)
	v_mfma_f32_16x16x32_bf16 v[94:97], v[238:241], v[198:201], v[94:97]
	v_mfma_f32_16x16x32_bf16 v[90:93], v[242:245], v[198:201], v[90:93]
	v_mfma_f32_16x16x32_bf16 v[86:89], v[246:249], v[198:201], v[86:89]
	v_mfma_f32_16x16x32_bf16 v[82:85], v[222:225], v[198:201], v[82:85]
	s_waitcnt vmcnt(1)
	ds_write_b128 v234, v[42:45] offset:20480
	s_waitcnt vmcnt(0)
	ds_write_b128 v234, v[46:49] offset:22528
	s_waitcnt lgkmcnt(9)
	v_mfma_f32_16x16x32_bf16 v[78:81], v[238:241], v[202:205], v[78:81]
	v_mfma_f32_16x16x32_bf16 v[74:77], v[242:245], v[202:205], v[74:77]
	v_mfma_f32_16x16x32_bf16 v[70:73], v[246:249], v[202:205], v[70:73]
	v_mfma_f32_16x16x32_bf16 v[66:69], v[222:225], v[202:205], v[66:69]
	s_waitcnt lgkmcnt(6)
	v_mfma_f32_16x16x32_bf16 v[62:65], v[238:241], v[206:209], v[62:65]
	v_mfma_f32_16x16x32_bf16 v[58:61], v[242:245], v[206:209], v[58:61]
	v_mfma_f32_16x16x32_bf16 v[54:57], v[246:249], v[206:209], v[54:57]
	v_mfma_f32_16x16x32_bf16 v[50:53], v[222:225], v[206:209], v[50:53]
	s_waitcnt lgkmcnt(0)
	s_barrier
; template <int MODE>
; __device__ void gemm_tile2(const u16* __restrict__ X, int lda, const u16* __restrict__ W, int ldb, int K,
;                            int m0, int n0, u16* __restrict__ outb, int vbase,
;                            const float* resid, float* outf, unsigned char* smem) {
;     ...
;   for (int kt2 = 0; kt2 < nk; kt2 += 2) {
; #pragma unroll
;     for (int h = 0; h < 2; ++h) {
;       const int kt = kt2 + h;
;       const u16* st = sbase + h * G2STAGE;
;       bf16x8 fw[4], fx[4];
; #pragma unroll
;       for (int j = 0; j < 4; ++j) fw[j] = *(const bf16x8*)(st + 256 * G2S + (ww * 64 + j * 16 + l15) * G2S + fsw);
; #pragma unroll
;       for (int i = 0; i < 4; ++i) fx[i] = *(const bf16x8*)(st + (wx * 128 + i * 16 + l15) * G2S + fsw);
;       __builtin_amdgcn_sched_barrier(0);
;       __builtin_amdgcn_s_setprio(1);
; #pragma unroll
;       for (int i = 0; i < 4; ++i) {
; #pragma unroll
;         for (int j = 0; j < 4; ++j) {
;           if (MODE == 1) acc[i][j] = mfma16(fx[i], fw[j], acc[i][j]);
;           else acc[i][j] = mfma16(fw[j], fx[i], acc[i][j]);
;         }
;       }
;       __builtin_amdgcn_s_setprio(0);
;       __builtin_amdgcn_sched_barrier(0);
; #pragma unroll
;       for (int i = 0; i < 4; ++i) fx[i] = *(const bf16x8*)(st + (wx * 128 + (i + 4) * 16 + l15) * G2S + fsw);
;       __builtin_amdgcn_sched_barrier(0);
;       if (kt + 1 < nk) G2_LSTORE(1 - h, 1 - h);
;       if (kt + 3 < nk) G2_GLOAD(1 - h, kt + 3);
;       __builtin_amdgcn_sched_barrier(0);
;       __builtin_amdgcn_s_setprio(1);
; #pragma unroll
;       for (int i = 0; i < 4; ++i) {
; #pragma unroll
;         for (int j = 0; j < 4; ++j) {
;           if (MODE == 1) acc[i + 4][j] = mfma16(fx[i], fw[j], acc[i + 4][j]);
;           else acc[i + 4][j] = mfma16(fw[j], fx[i], acc[i + 4][j]);
;         }
;       }
;       __builtin_amdgcn_s_setprio(0);
;       __syncthreads();
;     }
;   }
	s_mov_b32 s38, s35
	s_mov_b32 s35, s7
	s_mov_b32 s7, s6
	s_mov_b32 s6, s38
	ds_read_b128 v[178:181], v235 offset:16384
	ds_read_b128 v[182:185], v235 offset:17408
	ds_read_b128 v[186:189], v235 offset:18432
	ds_read_b128 v[190:193], v235 offset:19456
	ds_read_b128 v[194:197], v236
	ds_read_b128 v[198:201], v236 offset:1024
	ds_read_b128 v[202:205], v236 offset:2048
	ds_read_b128 v[206:209], v236 offset:3072
	s_waitcnt lgkmcnt(3)
	v_mfma_f32_16x16x32_bf16 v[174:177], v[178:181], v[194:197], v[174:177]
	v_mfma_f32_16x16x32_bf16 v[170:173], v[182:185], v[194:197], v[170:173]
	v_mfma_f32_16x16x32_bf16 v[166:169], v[186:189], v[194:197], v[166:169]
	v_mfma_f32_16x16x32_bf16 v[162:165], v[190:193], v[194:197], v[162:165]
	ds_read_b128 v[194:197], v236 offset:4096
	ds_read_b128 v[238:241], v232 offset:16384
	s_waitcnt lgkmcnt(4)
	v_mfma_f32_16x16x32_bf16 v[158:161], v[178:181], v[198:201], v[158:161]
	v_mfma_f32_16x16x32_bf16 v[154:157], v[182:185], v[198:201], v[154:157]
	v_mfma_f32_16x16x32_bf16 v[150:153], v[186:189], v[198:201], v[150:153]
	v_mfma_f32_16x16x32_bf16 v[146:149], v[190:193], v[198:201], v[146:149]
	ds_read_b128 v[198:201], v236 offset:5120
	ds_read_b128 v[242:245], v232 offset:17408
	s_waitcnt lgkmcnt(5)
	v_mfma_f32_16x16x32_bf16 v[142:145], v[178:181], v[202:205], v[142:145]
	v_mfma_f32_16x16x32_bf16 v[138:141], v[182:185], v[202:205], v[138:141]
	v_mfma_f32_16x16x32_bf16 v[134:137], v[186:189], v[202:205], v[134:137]
	v_mfma_f32_16x16x32_bf16 v[130:133], v[190:193], v[202:205], v[130:133]
	ds_read_b128 v[202:205], v236 offset:6144
	ds_read_b128 v[246:249], v232 offset:18432
	s_waitcnt lgkmcnt(6)
	v_mfma_f32_16x16x32_bf16 v[126:129], v[178:181], v[206:209], v[126:129]
	v_mfma_f32_16x16x32_bf16 v[122:125], v[182:185], v[206:209], v[122:125]
	v_mfma_f32_16x16x32_bf16 v[118:121], v[186:189], v[206:209], v[118:121]
	v_mfma_f32_16x16x32_bf16 v[114:117], v[190:193], v[206:209], v[114:117]
	ds_read_b128 v[206:209], v236 offset:7168
	ds_read_b128 v[222:225], v232 offset:19456
	s_sub_i32 s38, s35, s6
	v_add_u32_e32 v235, s38, v235
	v_add_u32_e32 v236, s38, v236
	s_waitcnt lgkmcnt(7)
	v_mfma_f32_16x16x32_bf16 v[110:113], v[178:181], v[194:197], v[110:113]
	v_mfma_f32_16x16x32_bf16 v[106:109], v[182:185], v[194:197], v[106:109]
	v_mfma_f32_16x16x32_bf16 v[102:105], v[186:189], v[194:197], v[102:105]
	v_mfma_f32_16x16x32_bf16 v[98:101], v[190:193], v[194:197], v[98:101]
	ds_read_b128 v[194:197], v237
	s_waitcnt lgkmcnt(6)
	v_mfma_f32_16x16x32_bf16 v[94:97], v[178:181], v[198:201], v[94:97]
	v_mfma_f32_16x16x32_bf16 v[90:93], v[182:185], v[198:201], v[90:93]
	v_mfma_f32_16x16x32_bf16 v[86:89], v[186:189], v[198:201], v[86:89]
	v_mfma_f32_16x16x32_bf16 v[82:85], v[190:193], v[198:201], v[82:85]
	ds_read_b128 v[198:201], v237 offset:1024
	s_waitcnt lgkmcnt(5)
	v_mfma_f32_16x16x32_bf16 v[78:81], v[178:181], v[202:205], v[78:81]
	v_mfma_f32_16x16x32_bf16 v[74:77], v[182:185], v[202:205], v[74:77]
	v_mfma_f32_16x16x32_bf16 v[70:73], v[186:189], v[202:205], v[70:73]
	v_mfma_f32_16x16x32_bf16 v[66:69], v[190:193], v[202:205], v[66:69]
	ds_read_b128 v[202:205], v237 offset:2048
	s_waitcnt lgkmcnt(4)
	v_mfma_f32_16x16x32_bf16 v[62:65], v[178:181], v[206:209], v[62:65]
	v_mfma_f32_16x16x32_bf16 v[58:61], v[182:185], v[206:209], v[58:61]
	v_mfma_f32_16x16x32_bf16 v[54:57], v[186:189], v[206:209], v[54:57]
	v_mfma_f32_16x16x32_bf16 v[50:53], v[190:193], v[206:209], v[50:53]
	ds_read_b128 v[206:209], v237 offset:3072
	s_barrier
	s_waitcnt lgkmcnt(3)
	v_mfma_f32_16x16x32_bf16 v[174:177], v[238:241], v[194:197], v[174:177]
	v_mfma_f32_16x16x32_bf16 v[170:173], v[242:245], v[194:197], v[170:173]
	v_mfma_f32_16x16x32_bf16 v[166:169], v[246:249], v[194:197], v[166:169]
	v_mfma_f32_16x16x32_bf16 v[162:165], v[222:225], v[194:197], v[162:165]
	ds_read_b128 v[194:197], v237 offset:4096
	s_waitcnt lgkmcnt(3)
	v_mfma_f32_16x16x32_bf16 v[158:161], v[238:241], v[198:201], v[158:161]
	v_mfma_f32_16x16x32_bf16 v[154:157], v[242:245], v[198:201], v[154:157]
	v_mfma_f32_16x16x32_bf16 v[150:153], v[246:249], v[198:201], v[150:153]
	v_mfma_f32_16x16x32_bf16 v[146:149], v[222:225], v[198:201], v[146:149]
	ds_read_b128 v[198:201], v237 offset:5120
	s_waitcnt lgkmcnt(3)
	v_mfma_f32_16x16x32_bf16 v[142:145], v[238:241], v[202:205], v[142:145]
	v_mfma_f32_16x16x32_bf16 v[138:141], v[242:245], v[202:205], v[138:141]
	v_mfma_f32_16x16x32_bf16 v[134:137], v[246:249], v[202:205], v[134:137]
	v_mfma_f32_16x16x32_bf16 v[130:133], v[222:225], v[202:205], v[130:133]
	ds_read_b128 v[202:205], v237 offset:6144
	s_waitcnt lgkmcnt(3)
	v_mfma_f32_16x16x32_bf16 v[126:129], v[238:241], v[206:209], v[126:129]
	v_mfma_f32_16x16x32_bf16 v[122:125], v[242:245], v[206:209], v[122:125]
	v_mfma_f32_16x16x32_bf16 v[118:121], v[246:249], v[206:209], v[118:121]
	v_mfma_f32_16x16x32_bf16 v[114:117], v[222:225], v[206:209], v[114:117]
	ds_read_b128 v[206:209], v237 offset:7168
	s_sub_i32 s38, s6, s7
	v_add_u32_e32 v232, s38, v232
	v_add_u32_e32 v237, s38, v237
	s_waitcnt lgkmcnt(3)
	v_mfma_f32_16x16x32_bf16 v[110:113], v[238:241], v[194:197], v[110:113]
	v_mfma_f32_16x16x32_bf16 v[106:109], v[242:245], v[194:197], v[106:109]
	v_mfma_f32_16x16x32_bf16 v[102:105], v[246:249], v[194:197], v[102:105]
	v_mfma_f32_16x16x32_bf16 v[98:101], v[222:225], v[194:197], v[98:101]
	s_waitcnt lgkmcnt(2)
	v_mfma_f32_16x16x32_bf16 v[94:97], v[238:241], v[198:201], v[94:97]
	v_mfma_f32_16x16x32_bf16 v[90:93], v[242:245], v[198:201], v[90:93]
	v_mfma_f32_16x16x32_bf16 v[86:89], v[246:249], v[198:201], v[86:89]
	v_mfma_f32_16x16x32_bf16 v[82:85], v[222:225], v[198:201], v[82:85]
	s_waitcnt lgkmcnt(1)
	v_mfma_f32_16x16x32_bf16 v[78:81], v[238:241], v[202:205], v[78:81]
	v_mfma_f32_16x16x32_bf16 v[74:77], v[242:245], v[202:205], v[74:77]
	v_mfma_f32_16x16x32_bf16 v[70:73], v[246:249], v[202:205], v[70:73]
	v_mfma_f32_16x16x32_bf16 v[66:69], v[222:225], v[202:205], v[66:69]
	s_waitcnt lgkmcnt(0)
	v_mfma_f32_16x16x32_bf16 v[62:65], v[238:241], v[206:209], v[62:65]
	v_mfma_f32_16x16x32_bf16 v[58:61], v[242:245], v[206:209], v[58:61]
	v_mfma_f32_16x16x32_bf16 v[54:57], v[246:249], v[206:209], v[54:57]
	v_mfma_f32_16x16x32_bf16 v[50:53], v[222:225], v[206:209], v[50:53]
	s_barrier
	s_mov_b32 s38, s35
	s_mov_b32 s35, s7
	s_mov_b32 s7, s6
	s_mov_b32 s6, s38
	s_nop 7

; __device__ __forceinline__ int otid() { int t = threadIdx.x; asm volatile("" : "+v"(t)); return t; }
; template <int MODE>
; __device__ void gemm_tile2(const u16* __restrict__ X, int lda, const u16* __restrict__ W, int ldb, int K,
;                            int m0, int n0, u16* __restrict__ outb, int vbase,
;                            const float* resid, float* outf, unsigned char* smem) {
;     ...
;   const int tid = otid(), lane = tid & 63, l15 = lane & 15, quad = lane >> 4;
;   const int wave = tid >> 6;
;   const int wx = wave >> 1, ww = wave & 1;
;   f32x4 acc[8][4];
; #pragma unroll
;   for (int i = 0; i < 8; ++i)
; #pragma unroll
;     for (int j = 0; j < 4; ++j) acc[i][j] = f32x4{0.f, 0.f, 0.f, 0.f};
;   u32x4 rx[2][4], rw[2][2];
;   const int lrow = tid >> 2, lkc = (tid & 3) * 8;
;   const int lsw = ((tid & 3) ^ ((0 - (lrow >> 2)) & 3)) * 8;
;   const int fsw = (quad ^ ((0 - (l15 >> 2)) & 3)) * 8;
;   const auto rsX = __builtin_amdgcn_make_buffer_rsrc((void*)(X + (size_t)m0 * lda), (short)0, 0x7fffffff, 0x00020000);
;   const auto rsW = __builtin_amdgcn_make_buffer_rsrc((void*)(W + (size_t)n0 * ldb), (short)0, 0x7fffffff, 0x00020000);
;   const int vox = (lrow * lda + lkc) * 2, vow = (lrow * ldb + lkc) * 2;
;   const int nk = K / 32;
;     ...
;   G2_GLOAD(0, 0);
;   G2_GLOAD(1, 1);
;   __syncthreads();
;   G2_LSTORE(0, 0);
;   G2_GLOAD(0, 2);
;   __syncthreads();
.LBB0_321:
	v_mov_b32_e32 v0, v210
	s_lshl_b32 s1, s31, 18
	s_lshl_b32 s6, s18, 19
	s_add_u32 s24, s36, s6
	s_addc_u32 s6, s37, 0
	s_and_b32 s25, s6, 0xffff
	s_add_u32 s40, s8, s1
	s_addc_u32 s1, s9, 0
	s_and_b32 s41, s1, 0xffff
	s_mov_b32 s42, s26
	s_mov_b32 s43, s27
	v_lshlrev_b32_e32 v230, 4, v0
	v_lshrrev_b32_e32 v231, 4, v0
	v_bfe_u32 v234, v0, 6, 1
	v_lshrrev_b32_e32 v2, 2, v0
	v_sub_u32_e32 v2, 0, v2
	v_lshrrev_b32_e32 v3, 4, v0
	v_xor_b32_e32 v2, v3, v2
	v_lshlrev_b32_e32 v2, 4, v2
	v_and_b32_e32 v2, 48, v2
	v_lshlrev_b32_e32 v4, 6, v0
	v_and_b32_e32 v5, 0x3c0, v4
	v_bfe_u32 v6, v0, 6, 1
	v_lshl_or_b32 v6, v6, 12, v2
	v_add_u32_e32 v236, v6, v5
	v_and_b32_e32 v4, 0xffffe3c0, v4
	v_add_u32_e32 v237, v2, v4
	v_xor_b32_e32 v233, 64, v236
	v_add_u32_e32 v233, 0x6000, v233
	v_xor_b32_e32 v232, 64, v237
	v_add_u32_e32 v232, 0x6000, v232
	v_and_b32_e32 v2, 3, v0
	v_bfe_u32 v221, v0, 2, 1
	v_lshrrev_b32_e32 v4, 3, v0
	v_lshrrev_b32_e32 v5, 2, v4
	v_sub_u32_e32 v5, 0, v5
	v_and_b32_e32 v5, 3, v5
	v_xor_b32_e32 v5, v2, v5
	v_lshlrev_b32_e32 v5, 4, v5
	v_lshl_or_b32 v5, v221, 6, v5
	v_lshl_or_b32 v218, v4, 11, v5
	v_add_u32_e32 v219, 0x10000, v218
	v_lshlrev_b32_e32 v2, 4, v2
	v_xor_b32_e32 v4, v4, v221
	v_lshl_or_b32 v220, v4, 6, v2
	buffer_load_dwordx4 v[2:5], v218, s[24:27], 0 offen
	buffer_load_dwordx4 v[6:9], v219, s[24:27], 0 offen
	buffer_load_dwordx4 v[10:13], v218, s[24:27], s27 offen
	buffer_load_dwordx4 v[14:17], v219, s[24:27], s27 offen
	buffer_load_dwordx4 v[18:21], v218, s[24:27], s77 offen
	buffer_load_dwordx4 v[22:25], v219, s[24:27], s77 offen
	buffer_load_dwordx4 v[26:29], v218, s[24:27], s78 offen
	buffer_load_dwordx4 v[30:33], v219, s[24:27], s78 offen
	buffer_load_dwordx4 v[34:37], v218, s[40:43], 0 offen
	buffer_load_dwordx4 v[38:41], v219, s[40:43], 0 offen
	buffer_load_dwordx4 v[42:45], v218, s[40:43], s27 offen
	buffer_load_dwordx4 v[46:49], v219, s[40:43], s27 offen
	v_add_u32_e32 v218, 0x80, v218
	v_add_u32_e32 v219, 0x80, v219
	v_mov_b32_e32 v50, 0
	v_mov_b32_e32 v51, 0
	v_mov_b32_e32 v52, 0
	v_mov_b32_e32 v53, 0
	v_mov_b32_e32 v54, 0
	v_mov_b32_e32 v55, 0
	v_mov_b32_e32 v56, 0
	v_mov_b32_e32 v57, 0
	v_mov_b32_e32 v58, 0
	v_mov_b32_e32 v59, 0
	v_mov_b32_e32 v60, 0
	v_mov_b32_e32 v61, 0
	v_mov_b32_e32 v62, 0
	v_mov_b32_e32 v63, 0
	v_mov_b32_e32 v64, 0
	v_mov_b32_e32 v65, 0
	v_mov_b32_e32 v66, 0
	v_mov_b32_e32 v67, 0
	v_mov_b32_e32 v68, 0
	v_mov_b32_e32 v69, 0
	v_mov_b32_e32 v70, 0
	v_mov_b32_e32 v71, 0
	v_mov_b32_e32 v72, 0
	v_mov_b32_e32 v73, 0
	v_mov_b32_e32 v74, 0
	v_mov_b32_e32 v75, 0
	v_mov_b32_e32 v76, 0
	v_mov_b32_e32 v77, 0
	v_mov_b32_e32 v78, 0
	v_mov_b32_e32 v79, 0
	v_mov_b32_e32 v80, 0
	v_mov_b32_e32 v81, 0
	v_mov_b32_e32 v82, 0
	v_mov_b32_e32 v83, 0
	v_mov_b32_e32 v84, 0
	v_mov_b32_e32 v85, 0
	v_mov_b32_e32 v86, 0
	v_mov_b32_e32 v87, 0
	v_mov_b32_e32 v88, 0
	v_mov_b32_e32 v89, 0
	v_mov_b32_e32 v90, 0
	v_mov_b32_e32 v91, 0
	v_mov_b32_e32 v92, 0
	v_mov_b32_e32 v93, 0
	v_mov_b32_e32 v94, 0
	v_mov_b32_e32 v95, 0
	v_mov_b32_e32 v96, 0
	v_mov_b32_e32 v97, 0
	v_mov_b32_e32 v98, 0
	v_mov_b32_e32 v99, 0
	v_mov_b32_e32 v100, 0
	v_mov_b32_e32 v101, 0
	v_mov_b32_e32 v102, 0
	v_mov_b32_e32 v103, 0
	v_mov_b32_e32 v104, 0
	v_mov_b32_e32 v105, 0
	v_mov_b32_e32 v106, 0
	v_mov_b32_e32 v107, 0
	v_mov_b32_e32 v108, 0
	v_mov_b32_e32 v109, 0
	v_mov_b32_e32 v110, 0
	v_mov_b32_e32 v111, 0
	v_mov_b32_e32 v112, 0
	v_mov_b32_e32 v113, 0
	v_mov_b32_e32 v114, 0
	v_mov_b32_e32 v115, 0
	v_mov_b32_e32 v116, 0
	v_mov_b32_e32 v117, 0
	v_mov_b32_e32 v118, 0
	v_mov_b32_e32 v119, 0
	v_mov_b32_e32 v120, 0
	v_mov_b32_e32 v121, 0
	v_mov_b32_e32 v122, 0
	v_mov_b32_e32 v123, 0
	v_mov_b32_e32 v124, 0
	v_mov_b32_e32 v125, 0
	v_mov_b32_e32 v126, 0
	v_mov_b32_e32 v127, 0
	v_mov_b32_e32 v128, 0
	v_mov_b32_e32 v129, 0
	v_mov_b32_e32 v130, 0
	v_mov_b32_e32 v131, 0
	v_mov_b32_e32 v132, 0
	v_mov_b32_e32 v133, 0
	v_mov_b32_e32 v134, 0
	v_mov_b32_e32 v135, 0
	v_mov_b32_e32 v136, 0
	v_mov_b32_e32 v137, 0
	v_mov_b32_e32 v138, 0
	v_mov_b32_e32 v139, 0
	v_mov_b32_e32 v140, 0
	v_mov_b32_e32 v141, 0
	v_mov_b32_e32 v142, 0
	v_mov_b32_e32 v143, 0
	v_mov_b32_e32 v144, 0
	v_mov_b32_e32 v145, 0
	v_mov_b32_e32 v146, 0
	v_mov_b32_e32 v147, 0
	v_mov_b32_e32 v148, 0
	v_mov_b32_e32 v149, 0
	v_mov_b32_e32 v150, 0
	v_mov_b32_e32 v151, 0
	v_mov_b32_e32 v152, 0
	v_mov_b32_e32 v153, 0
	v_mov_b32_e32 v154, 0
	v_mov_b32_e32 v155, 0
	v_mov_b32_e32 v156, 0
	v_mov_b32_e32 v157, 0
	v_mov_b32_e32 v158, 0
	v_mov_b32_e32 v159, 0
	v_mov_b32_e32 v160, 0
	v_mov_b32_e32 v161, 0
	v_mov_b32_e32 v162, 0
	v_mov_b32_e32 v163, 0
	v_mov_b32_e32 v164, 0
	v_mov_b32_e32 v165, 0
	v_mov_b32_e32 v166, 0
	v_mov_b32_e32 v167, 0
	v_mov_b32_e32 v168, 0
	v_mov_b32_e32 v169, 0
	v_mov_b32_e32 v170, 0
	v_mov_b32_e32 v171, 0
	v_mov_b32_e32 v172, 0
	v_mov_b32_e32 v173, 0
	v_mov_b32_e32 v174, 0
	v_mov_b32_e32 v175, 0
	v_mov_b32_e32 v176, 0
	v_mov_b32_e32 v177, 0
	s_mov_b32 s1, 0
	s_mov_b32 s6, 0x6000
	s_mov_b32 s7, 0xc000
	s_mov_b32 s0, 0
	v_mad_i32_i24 v235, v221, s6, v220
	s_barrier
	s_waitcnt vmcnt(11)
	ds_write_b128 v235, v[2:5]
	s_waitcnt vmcnt(10)
	ds_write_b128 v235, v[6:9] offset:2048
	s_waitcnt vmcnt(9)
	ds_write_b128 v235, v[10:13] offset:4096
	s_waitcnt vmcnt(8)
	ds_write_b128 v235, v[14:17] offset:6144
	s_waitcnt vmcnt(7)
	ds_write_b128 v235, v[18:21] offset:8192
	s_waitcnt vmcnt(6)
	ds_write_b128 v235, v[22:25] offset:10240
	s_waitcnt vmcnt(5)
	ds_write_b128 v235, v[26:29] offset:12288
	s_waitcnt vmcnt(4)
	ds_write_b128 v235, v[30:33] offset:14336
	s_waitcnt vmcnt(3)
	ds_write_b128 v235, v[34:37] offset:16384
	s_waitcnt vmcnt(2)
	ds_write_b128 v235, v[38:41] offset:18432
	s_waitcnt vmcnt(1)
	ds_write_b128 v235, v[42:45] offset:20480
	s_waitcnt vmcnt(0)
	ds_write_b128 v235, v[46:49] offset:22528
	buffer_load_dwordx4 v[2:5], v218, s[24:27], 0 offen
	buffer_load_dwordx4 v[6:9], v219, s[24:27], 0 offen
	buffer_load_dwordx4 v[10:13], v218, s[24:27], s27 offen
	buffer_load_dwordx4 v[14:17], v219, s[24:27], s27 offen
	buffer_load_dwordx4 v[18:21], v218, s[24:27], s77 offen
	buffer_load_dwordx4 v[22:25], v219, s[24:27], s77 offen
	buffer_load_dwordx4 v[26:29], v218, s[24:27], s78 offen
	buffer_load_dwordx4 v[30:33], v219, s[24:27], s78 offen
	buffer_load_dwordx4 v[34:37], v218, s[40:43], 0 offen
	buffer_load_dwordx4 v[38:41], v219, s[40:43], 0 offen
	buffer_load_dwordx4 v[42:45], v218, s[40:43], s27 offen
	buffer_load_dwordx4 v[46:49], v219, s[40:43], s27 offen
	v_add_u32_e32 v218, 0x80, v218
	v_add_u32_e32 v219, 0x80, v219
	s_waitcnt lgkmcnt(0)
	s_barrier
	ds_read_b128 v[178:181], v236 offset:16384
	ds_read_b128 v[182:185], v236 offset:17408
	ds_read_b128 v[186:189], v236 offset:18432
	ds_read_b128 v[190:193], v236 offset:19456
	ds_read_b128 v[194:197], v237
	ds_read_b128 v[198:201], v237 offset:1024
	ds_read_b128 v[202:205], v237 offset:2048
	ds_read_b128 v[206:209], v237 offset:3072
; template <int MODE>
; __device__ void gemm_tile2(const u16* __restrict__ X, int lda, const u16* __restrict__ W, int ldb, int K,
;                            int m0, int n0, u16* __restrict__ outb, int vbase,
;                            const float* resid, float* outf, unsigned char* smem) {
;     ...
;   for (int kt2 = 0; kt2 < nk; kt2 += 2) {
; #pragma unroll
;     for (int h = 0; h < 2; ++h) {
;       const int kt = kt2 + h;
;       const u16* st = sbase + h * G2STAGE;
;       bf16x8 fw[4], fx[4];
; #pragma unroll
;       for (int j = 0; j < 4; ++j) fw[j] = *(const bf16x8*)(st + 256 * G2S + (ww * 64 + j * 16 + l15) * G2S + fsw);
; #pragma unroll
;       for (int i = 0; i < 4; ++i) fx[i] = *(const bf16x8*)(st + (wx * 128 + i * 16 + l15) * G2S + fsw);
;       __builtin_amdgcn_sched_barrier(0);
;       __builtin_amdgcn_s_setprio(1);
; #pragma unroll
;       for (int i = 0; i < 4; ++i) {
; #pragma unroll
;         for (int j = 0; j < 4; ++j) {
;           if (MODE == 1) acc[i][j] = mfma16(fx[i], fw[j], acc[i][j]);
;           else acc[i][j] = mfma16(fw[j], fx[i], acc[i][j]);
;         }
;       }
;       __builtin_amdgcn_s_setprio(0);
;       __builtin_amdgcn_sched_barrier(0);
; #pragma unroll
;       for (int i = 0; i < 4; ++i) fx[i] = *(const bf16x8*)(st + (wx * 128 + (i + 4) * 16 + l15) * G2S + fsw);
;       __builtin_amdgcn_sched_barrier(0);
;       if (kt + 1 < nk) G2_LSTORE(1 - h, 1 - h);
;       if (kt + 3 < nk) G2_GLOAD(1 - h, kt + 3);
;       __builtin_amdgcn_sched_barrier(0);
;       __builtin_amdgcn_s_setprio(1);
; #pragma unroll
;       for (int i = 0; i < 4; ++i) {
; #pragma unroll
;         for (int j = 0; j < 4; ++j) {
;           if (MODE == 1) acc[i + 4][j] = mfma16(fx[i], fw[j], acc[i + 4][j]);
;           else acc[i + 4][j] = mfma16(fw[j], fx[i], acc[i + 4][j]);
;         }
;       }
;       __builtin_amdgcn_s_setprio(0);
;       __syncthreads();
;     }
;   }
.Lf1_loop:
	s_waitcnt lgkmcnt(3)
	v_mfma_f32_16x16x32_bf16 v[174:177], v[194:197], v[178:181], v[174:177]
	v_mfma_f32_16x16x32_bf16 v[170:173], v[194:197], v[182:185], v[170:173]
	v_mfma_f32_16x16x32_bf16 v[166:169], v[194:197], v[186:189], v[166:169]
	v_mfma_f32_16x16x32_bf16 v[162:165], v[194:197], v[190:193], v[162:165]
	ds_read_b128 v[194:197], v237 offset:4096
	ds_read_b128 v[238:241], v233 offset:16384
	s_waitcnt lgkmcnt(4)
	v_mfma_f32_16x16x32_bf16 v[158:161], v[198:201], v[178:181], v[158:161]
	v_mfma_f32_16x16x32_bf16 v[154:157], v[198:201], v[182:185], v[154:157]
	v_mfma_f32_16x16x32_bf16 v[150:153], v[198:201], v[186:189], v[150:153]
	v_mfma_f32_16x16x32_bf16 v[146:149], v[198:201], v[190:193], v[146:149]
	ds_read_b128 v[198:201], v237 offset:5120
	ds_read_b128 v[242:245], v233 offset:17408
	s_waitcnt lgkmcnt(5)
	v_mfma_f32_16x16x32_bf16 v[142:145], v[202:205], v[178:181], v[142:145]
	v_mfma_f32_16x16x32_bf16 v[138:141], v[202:205], v[182:185], v[138:141]
	v_mfma_f32_16x16x32_bf16 v[134:137], v[202:205], v[186:189], v[134:137]
	v_mfma_f32_16x16x32_bf16 v[130:133], v[202:205], v[190:193], v[130:133]
	ds_read_b128 v[202:205], v237 offset:6144
	ds_read_b128 v[246:249], v233 offset:18432
	s_waitcnt lgkmcnt(6)
	v_mfma_f32_16x16x32_bf16 v[126:129], v[206:209], v[178:181], v[126:129]
	v_mfma_f32_16x16x32_bf16 v[122:125], v[206:209], v[182:185], v[122:125]
	v_mfma_f32_16x16x32_bf16 v[118:121], v[206:209], v[186:189], v[118:121]
	v_mfma_f32_16x16x32_bf16 v[114:117], v[206:209], v[190:193], v[114:117]
	ds_read_b128 v[206:209], v237 offset:7168
	ds_read_b128 v[222:225], v233 offset:19456
	s_sub_i32 s35, s7, s1
	v_add_u32_e32 v236, s35, v236
	v_add_u32_e32 v237, s35, v237
	s_waitcnt lgkmcnt(7)
	v_mfma_f32_16x16x32_bf16 v[110:113], v[194:197], v[178:181], v[110:113]
	v_mfma_f32_16x16x32_bf16 v[106:109], v[194:197], v[182:185], v[106:109]
	v_mfma_f32_16x16x32_bf16 v[102:105], v[194:197], v[186:189], v[102:105]
	v_mfma_f32_16x16x32_bf16 v[98:101], v[194:197], v[190:193], v[98:101]
	ds_read_b128 v[194:197], v232
	s_waitcnt lgkmcnt(6)
	v_mfma_f32_16x16x32_bf16 v[94:97], v[198:201], v[178:181], v[94:97]
	v_mfma_f32_16x16x32_bf16 v[90:93], v[198:201], v[182:185], v[90:93]
	v_mfma_f32_16x16x32_bf16 v[86:89], v[198:201], v[186:189], v[86:89]
	v_mfma_f32_16x16x32_bf16 v[82:85], v[198:201], v[190:193], v[82:85]
	ds_read_b128 v[198:201], v232 offset:1024
	s_waitcnt lgkmcnt(5)
	v_mfma_f32_16x16x32_bf16 v[78:81], v[202:205], v[178:181], v[78:81]
	v_mfma_f32_16x16x32_bf16 v[74:77], v[202:205], v[182:185], v[74:77]
	v_mfma_f32_16x16x32_bf16 v[70:73], v[202:205], v[186:189], v[70:73]
	v_mfma_f32_16x16x32_bf16 v[66:69], v[202:205], v[190:193], v[66:69]
	ds_read_b128 v[202:205], v232 offset:2048
	s_waitcnt lgkmcnt(4)
	v_mfma_f32_16x16x32_bf16 v[62:65], v[206:209], v[178:181], v[62:65]
	v_mfma_f32_16x16x32_bf16 v[58:61], v[206:209], v[182:185], v[58:61]
	v_mfma_f32_16x16x32_bf16 v[54:57], v[206:209], v[186:189], v[54:57]
	v_mfma_f32_16x16x32_bf16 v[50:53], v[206:209], v[190:193], v[50:53]
	ds_read_b128 v[206:209], v232 offset:3072
	s_sub_i32 s35, s1, s7
	v_mad_i32_i24 v235, v221, s35, v220
	v_add_u32_e32 v235, s7, v235
	s_barrier
	s_waitcnt lgkmcnt(3)
	v_mfma_f32_16x16x32_bf16 v[174:177], v[194:197], v[238:241], v[174:177]
	v_mfma_f32_16x16x32_bf16 v[170:173], v[194:197], v[242:245], v[170:173]
	v_mfma_f32_16x16x32_bf16 v[166:169], v[194:197], v[246:249], v[166:169]
	v_mfma_f32_16x16x32_bf16 v[162:165], v[194:197], v[222:225], v[162:165]
	ds_read_b128 v[194:197], v232 offset:4096
	s_waitcnt vmcnt(11)
	ds_write_b128 v235, v[2:5]
	s_waitcnt vmcnt(10)
	ds_write_b128 v235, v[6:9] offset:2048
	buffer_load_dwordx4 v[2:5], v218, s[24:27], 0 offen
	buffer_load_dwordx4 v[6:9], v219, s[24:27], 0 offen
	s_waitcnt lgkmcnt(5)
	v_mfma_f32_16x16x32_bf16 v[158:161], v[198:201], v[238:241], v[158:161]
	v_mfma_f32_16x16x32_bf16 v[154:157], v[198:201], v[242:245], v[154:157]
	v_mfma_f32_16x16x32_bf16 v[150:153], v[198:201], v[246:249], v[150:153]
	v_mfma_f32_16x16x32_bf16 v[146:149], v[198:201], v[222:225], v[146:149]
	ds_read_b128 v[198:201], v232 offset:5120
	s_waitcnt vmcnt(11)
	ds_write_b128 v235, v[10:13] offset:4096
	s_waitcnt vmcnt(10)
	ds_write_b128 v235, v[14:17] offset:6144
	buffer_load_dwordx4 v[10:13], v218, s[24:27], s27 offen
	buffer_load_dwordx4 v[14:17], v219, s[24:27], s27 offen
	s_waitcnt lgkmcnt(7)
	v_mfma_f32_16x16x32_bf16 v[142:145], v[202:205], v[238:241], v[142:145]
	v_mfma_f32_16x16x32_bf16 v[138:141], v[202:205], v[242:245], v[138:141]
	v_mfma_f32_16x16x32_bf16 v[134:137], v[202:205], v[246:249], v[134:137]
	v_mfma_f32_16x16x32_bf16 v[130:133], v[202:205], v[222:225], v[130:133]
	ds_read_b128 v[202:205], v232 offset:6144
	s_waitcnt vmcnt(11)
	ds_write_b128 v235, v[18:21] offset:8192
	s_waitcnt vmcnt(10)
	ds_write_b128 v235, v[22:25] offset:10240
	buffer_load_dwordx4 v[18:21], v218, s[24:27], s77 offen
	buffer_load_dwordx4 v[22:25], v219, s[24:27], s77 offen
	s_waitcnt lgkmcnt(9)
	v_mfma_f32_16x16x32_bf16 v[126:129], v[206:209], v[238:241], v[126:129]
	v_mfma_f32_16x16x32_bf16 v[122:125], v[206:209], v[242:245], v[122:125]
	v_mfma_f32_16x16x32_bf16 v[118:121], v[206:209], v[246:249], v[118:121]
	v_mfma_f32_16x16x32_bf16 v[114:117], v[206:209], v[222:225], v[114:117]
	ds_read_b128 v[206:209], v232 offset:7168
	s_sub_i32 s35, s1, s6
	v_add_u32_e32 v233, s35, v233
	v_add_u32_e32 v232, s35, v232
	s_waitcnt vmcnt(11)
	ds_write_b128 v235, v[26:29] offset:12288
	s_waitcnt vmcnt(10)
	ds_write_b128 v235, v[30:33] offset:14336
	buffer_load_dwordx4 v[26:29], v218, s[24:27], s78 offen
	buffer_load_dwordx4 v[30:33], v219, s[24:27], s78 offen
	s_waitcnt lgkmcnt(11)
; template <int MODE>
; __device__ void gemm_tile2(const u16* __restrict__ X, int lda, const u16* __restrict__ W, int ldb, int K,
;                            int m0, int n0, u16* __restrict__ outb, int vbase,
;                            const float* resid, float* outf, unsigned char* smem) {
;     ...
;   for (int kt2 = 0; kt2 < nk; kt2 += 2) {
; #pragma unroll
;     for (int h = 0; h < 2; ++h) {
;       const int kt = kt2 + h;
;       const u16* st = sbase + h * G2STAGE;
;       bf16x8 fw[4], fx[4];
; #pragma unroll
;       for (int j = 0; j < 4; ++j) fw[j] = *(const bf16x8*)(st + 256 * G2S + (ww * 64 + j * 16 + l15) * G2S + fsw);
; #pragma unroll
;       for (int i = 0; i < 4; ++i) fx[i] = *(const bf16x8*)(st + (wx * 128 + i * 16 + l15) * G2S + fsw);
;       __builtin_amdgcn_sched_barrier(0);
;       __builtin_amdgcn_s_setprio(1);
; #pragma unroll
;       for (int i = 0; i < 4; ++i) {
; #pragma unroll
;         for (int j = 0; j < 4; ++j) {
;           if (MODE == 1) acc[i][j] = mfma16(fx[i], fw[j], acc[i][j]);
;           else acc[i][j] = mfma16(fw[j], fx[i], acc[i][j]);
;         }
;       }
;       __builtin_amdgcn_s_setprio(0);
;       __builtin_amdgcn_sched_barrier(0);
; #pragma unroll
;       for (int i = 0; i < 4; ++i) fx[i] = *(const bf16x8*)(st + (wx * 128 + (i + 4) * 16 + l15) * G2S + fsw);
;       __builtin_amdgcn_sched_barrier(0);
;       if (kt + 1 < nk) G2_LSTORE(1 - h, 1 - h);
;       if (kt + 3 < nk) G2_GLOAD(1 - h, kt + 3);
;       __builtin_amdgcn_sched_barrier(0);
;       __builtin_amdgcn_s_setprio(1);
; #pragma unroll
;       for (int i = 0; i < 4; ++i) {
; #pragma unroll
;         for (int j = 0; j < 4; ++j) {
;           if (MODE == 1) acc[i + 4][j] = mfma16(fx[i], fw[j], acc[i + 4][j]);
;           else acc[i + 4][j] = mfma16(fw[j], fx[i], acc[i + 4][j]);
;         }
;       }
;       __builtin_amdgcn_s_setprio(0);
;       __syncthreads();
;     }
;   }
	v_mfma_f32_16x16x32_bf16 v[110:113], v[194:197], v[238:241], v[110:113]
	v_mfma_f32_16x16x32_bf16 v[106:109], v[194:197], v[242:245], v[106:109]
	v_mfma_f32_16x16x32_bf16 v[102:105], v[194:197], v[246:249], v[102:105]
	v_mfma_f32_16x16x32_bf16 v[98:101], v[194:197], v[222:225], v[98:101]
	s_waitcnt vmcnt(11)
	ds_write_b128 v235, v[34:37] offset:16384
	s_waitcnt vmcnt(10)
	ds_write_b128 v235, v[38:41] offset:18432
	buffer_load_dwordx4 v[34:37], v218, s[40:43], 0 offen
	buffer_load_dwordx4 v[38:41], v219, s[40:43], 0 offen
	s_waitcnt lgkmcnt(10)
	v_mfma_f32_16x16x32_bf16 v[94:97], v[198:201], v[238:241], v[94:97]
	v_mfma_f32_16x16x32_bf16 v[90:93], v[198:201], v[242:245], v[90:93]
	v_mfma_f32_16x16x32_bf16 v[86:89], v[198:201], v[246:249], v[86:89]
	v_mfma_f32_16x16x32_bf16 v[82:85], v[198:201], v[222:225], v[82:85]
	s_waitcnt vmcnt(11)
	ds_write_b128 v235, v[42:45] offset:20480
	s_waitcnt vmcnt(10)
	ds_write_b128 v235, v[46:49] offset:22528
	buffer_load_dwordx4 v[42:45], v218, s[40:43], s27 offen
	buffer_load_dwordx4 v[46:49], v219, s[40:43], s27 offen
	s_waitcnt lgkmcnt(9)
	v_mfma_f32_16x16x32_bf16 v[78:81], v[202:205], v[238:241], v[78:81]
	v_mfma_f32_16x16x32_bf16 v[74:77], v[202:205], v[242:245], v[74:77]
	v_mfma_f32_16x16x32_bf16 v[70:73], v[202:205], v[246:249], v[70:73]
	v_mfma_f32_16x16x32_bf16 v[66:69], v[202:205], v[222:225], v[66:69]
	s_waitcnt lgkmcnt(6)
	v_mfma_f32_16x16x32_bf16 v[62:65], v[206:209], v[238:241], v[62:65]
	v_mfma_f32_16x16x32_bf16 v[58:61], v[206:209], v[242:245], v[58:61]
	v_mfma_f32_16x16x32_bf16 v[54:57], v[206:209], v[246:249], v[54:57]
	v_mfma_f32_16x16x32_bf16 v[50:53], v[206:209], v[222:225], v[50:53]
	v_add_u32_e32 v218, 0x80, v218
	v_add_u32_e32 v219, 0x80, v219
	s_waitcnt lgkmcnt(0)
	s_barrier
	s_mov_b32 s35, s7
	s_mov_b32 s7, s6
	s_mov_b32 s6, s1
	s_mov_b32 s1, s35
	ds_read_b128 v[178:181], v236 offset:16384
	ds_read_b128 v[182:185], v236 offset:17408
	ds_read_b128 v[186:189], v236 offset:18432
	ds_read_b128 v[190:193], v236 offset:19456
	ds_read_b128 v[194:197], v237
	ds_read_b128 v[198:201], v237 offset:1024
	ds_read_b128 v[202:205], v237 offset:2048
	ds_read_b128 v[206:209], v237 offset:3072
	s_add_u32 s0, s0, 1
	s_cmp_lt_u32 s0, 14
	s_cbranch_scc1 .Lf1_loop
	s_waitcnt lgkmcnt(3)
	v_mfma_f32_16x16x32_bf16 v[174:177], v[194:197], v[178:181], v[174:177]
	v_mfma_f32_16x16x32_bf16 v[170:173], v[194:197], v[182:185], v[170:173]
	v_mfma_f32_16x16x32_bf16 v[166:169], v[194:197], v[186:189], v[166:169]
	v_mfma_f32_16x16x32_bf16 v[162:165], v[194:197], v[190:193], v[162:165]
	ds_read_b128 v[194:197], v237 offset:4096
	ds_read_b128 v[238:241], v233 offset:16384
	s_waitcnt lgkmcnt(4)
	v_mfma_f32_16x16x32_bf16 v[158:161], v[198:201], v[178:181], v[158:161]
	v_mfma_f32_16x16x32_bf16 v[154:157], v[198:201], v[182:185], v[154:157]
	v_mfma_f32_16x16x32_bf16 v[150:153], v[198:201], v[186:189], v[150:153]
	v_mfma_f32_16x16x32_bf16 v[146:149], v[198:201], v[190:193], v[146:149]
	ds_read_b128 v[198:201], v237 offset:5120
	ds_read_b128 v[242:245], v233 offset:17408
	s_waitcnt lgkmcnt(5)
	v_mfma_f32_16x16x32_bf16 v[142:145], v[202:205], v[178:181], v[142:145]
	v_mfma_f32_16x16x32_bf16 v[138:141], v[202:205], v[182:185], v[138:141]
	v_mfma_f32_16x16x32_bf16 v[134:137], v[202:205], v[186:189], v[134:137]
	v_mfma_f32_16x16x32_bf16 v[130:133], v[202:205], v[190:193], v[130:133]
	ds_read_b128 v[202:205], v237 offset:6144
	ds_read_b128 v[246:249], v233 offset:18432
	s_waitcnt lgkmcnt(6)
	v_mfma_f32_16x16x32_bf16 v[126:129], v[206:209], v[178:181], v[126:129]
	v_mfma_f32_16x16x32_bf16 v[122:125], v[206:209], v[182:185], v[122:125]
	v_mfma_f32_16x16x32_bf16 v[118:121], v[206:209], v[186:189], v[118:121]
	v_mfma_f32_16x16x32_bf16 v[114:117], v[206:209], v[190:193], v[114:117]
	ds_read_b128 v[206:209], v237 offset:7168
	ds_read_b128 v[222:225], v233 offset:19456
	s_sub_i32 s35, s7, s1
	v_add_u32_e32 v236, s35, v236
	v_add_u32_e32 v237, s35, v237
	s_waitcnt lgkmcnt(7)
	v_mfma_f32_16x16x32_bf16 v[110:113], v[194:197], v[178:181], v[110:113]
	v_mfma_f32_16x16x32_bf16 v[106:109], v[194:197], v[182:185], v[106:109]
	v_mfma_f32_16x16x32_bf16 v[102:105], v[194:197], v[186:189], v[102:105]
	v_mfma_f32_16x16x32_bf16 v[98:101], v[194:197], v[190:193], v[98:101]
	ds_read_b128 v[194:197], v232
	s_waitcnt lgkmcnt(6)
	v_mfma_f32_16x16x32_bf16 v[94:97], v[198:201], v[178:181], v[94:97]
	v_mfma_f32_16x16x32_bf16 v[90:93], v[198:201], v[182:185], v[90:93]
	v_mfma_f32_16x16x32_bf16 v[86:89], v[198:201], v[186:189], v[86:89]
	v_mfma_f32_16x16x32_bf16 v[82:85], v[198:201], v[190:193], v[82:85]
	ds_read_b128 v[198:201], v232 offset:1024
	s_waitcnt lgkmcnt(5)
	v_mfma_f32_16x16x32_bf16 v[78:81], v[202:205], v[178:181], v[78:81]
	v_mfma_f32_16x16x32_bf16 v[74:77], v[202:205], v[182:185], v[74:77]
	v_mfma_f32_16x16x32_bf16 v[70:73], v[202:205], v[186:189], v[70:73]
	v_mfma_f32_16x16x32_bf16 v[66:69], v[202:205], v[190:193], v[66:69]
	ds_read_b128 v[202:205], v232 offset:2048
	s_waitcnt lgkmcnt(4)
	v_mfma_f32_16x16x32_bf16 v[62:65], v[206:209], v[178:181], v[62:65]
	v_mfma_f32_16x16x32_bf16 v[58:61], v[206:209], v[182:185], v[58:61]
	v_mfma_f32_16x16x32_bf16 v[54:57], v[206:209], v[186:189], v[54:57]
	v_mfma_f32_16x16x32_bf16 v[50:53], v[206:209], v[190:193], v[50:53]
	ds_read_b128 v[206:209], v232 offset:3072
	s_sub_i32 s35, s1, s7
	v_mad_i32_i24 v235, v221, s35, v220
	v_add_u32_e32 v235, s7, v235
	s_barrier
; template <int MODE>
; __device__ void gemm_tile2(const u16* __restrict__ X, int lda, const u16* __restrict__ W, int ldb, int K,
;                            int m0, int n0, u16* __restrict__ outb, int vbase,
;                            const float* resid, float* outf, unsigned char* smem) {
;     ...
;   for (int kt2 = 0; kt2 < nk; kt2 += 2) {
; #pragma unroll
;     for (int h = 0; h < 2; ++h) {
;       const int kt = kt2 + h;
;       const u16* st = sbase + h * G2STAGE;
;       bf16x8 fw[4], fx[4];
; #pragma unroll
;       for (int j = 0; j < 4; ++j) fw[j] = *(const bf16x8*)(st + 256 * G2S + (ww * 64 + j * 16 + l15) * G2S + fsw);
; #pragma unroll
;       for (int i = 0; i < 4; ++i) fx[i] = *(const bf16x8*)(st + (wx * 128 + i * 16 + l15) * G2S + fsw);
;       __builtin_amdgcn_sched_barrier(0);
;       __builtin_amdgcn_s_setprio(1);
; #pragma unroll
;       for (int i = 0; i < 4; ++i) {
; #pragma unroll
;         for (int j = 0; j < 4; ++j) {
;           if (MODE == 1) acc[i][j] = mfma16(fx[i], fw[j], acc[i][j]);
;           else acc[i][j] = mfma16(fw[j], fx[i], acc[i][j]);
;         }
;       }
;       __builtin_amdgcn_s_setprio(0);
;       __builtin_amdgcn_sched_barrier(0);
; #pragma unroll
;       for (int i = 0; i < 4; ++i) fx[i] = *(const bf16x8*)(st + (wx * 128 + (i + 4) * 16 + l15) * G2S + fsw);
;       __builtin_amdgcn_sched_barrier(0);
;       if (kt + 1 < nk) G2_LSTORE(1 - h, 1 - h);
;       if (kt + 3 < nk) G2_GLOAD(1 - h, kt + 3);
;       __builtin_amdgcn_sched_barrier(0);
;       __builtin_amdgcn_s_setprio(1);
; #pragma unroll
;       for (int i = 0; i < 4; ++i) {
; #pragma unroll
;         for (int j = 0; j < 4; ++j) {
;           if (MODE == 1) acc[i + 4][j] = mfma16(fx[i], fw[j], acc[i + 4][j]);
;           else acc[i + 4][j] = mfma16(fw[j], fx[i], acc[i + 4][j]);
;         }
;       }
;       __builtin_amdgcn_s_setprio(0);
;       __syncthreads();
;     }
;   }
	s_waitcnt lgkmcnt(3)
	v_mfma_f32_16x16x32_bf16 v[174:177], v[194:197], v[238:241], v[174:177]
	v_mfma_f32_16x16x32_bf16 v[170:173], v[194:197], v[242:245], v[170:173]
	v_mfma_f32_16x16x32_bf16 v[166:169], v[194:197], v[246:249], v[166:169]
	v_mfma_f32_16x16x32_bf16 v[162:165], v[194:197], v[222:225], v[162:165]
	ds_read_b128 v[194:197], v232 offset:4096
	s_waitcnt vmcnt(11)
	ds_write_b128 v235, v[2:5]
	s_waitcnt vmcnt(10)
	ds_write_b128 v235, v[6:9] offset:2048
	s_waitcnt lgkmcnt(5)
	v_mfma_f32_16x16x32_bf16 v[158:161], v[198:201], v[238:241], v[158:161]
	v_mfma_f32_16x16x32_bf16 v[154:157], v[198:201], v[242:245], v[154:157]
	v_mfma_f32_16x16x32_bf16 v[150:153], v[198:201], v[246:249], v[150:153]
	v_mfma_f32_16x16x32_bf16 v[146:149], v[198:201], v[222:225], v[146:149]
	ds_read_b128 v[198:201], v232 offset:5120
	s_waitcnt vmcnt(9)
	ds_write_b128 v235, v[10:13] offset:4096
	s_waitcnt vmcnt(8)
	ds_write_b128 v235, v[14:17] offset:6144
	s_waitcnt lgkmcnt(7)
	v_mfma_f32_16x16x32_bf16 v[142:145], v[202:205], v[238:241], v[142:145]
	v_mfma_f32_16x16x32_bf16 v[138:141], v[202:205], v[242:245], v[138:141]
	v_mfma_f32_16x16x32_bf16 v[134:137], v[202:205], v[246:249], v[134:137]
	v_mfma_f32_16x16x32_bf16 v[130:133], v[202:205], v[222:225], v[130:133]
	ds_read_b128 v[202:205], v232 offset:6144
	s_waitcnt vmcnt(7)
	ds_write_b128 v235, v[18:21] offset:8192
	s_waitcnt vmcnt(6)
	ds_write_b128 v235, v[22:25] offset:10240
	s_waitcnt lgkmcnt(9)
	v_mfma_f32_16x16x32_bf16 v[126:129], v[206:209], v[238:241], v[126:129]
	v_mfma_f32_16x16x32_bf16 v[122:125], v[206:209], v[242:245], v[122:125]
	v_mfma_f32_16x16x32_bf16 v[118:121], v[206:209], v[246:249], v[118:121]
	v_mfma_f32_16x16x32_bf16 v[114:117], v[206:209], v[222:225], v[114:117]
	ds_read_b128 v[206:209], v232 offset:7168
	s_sub_i32 s35, s1, s6
	v_add_u32_e32 v233, s35, v233
	v_add_u32_e32 v232, s35, v232
	s_waitcnt vmcnt(5)
	ds_write_b128 v235, v[26:29] offset:12288
	s_waitcnt vmcnt(4)
	ds_write_b128 v235, v[30:33] offset:14336
	s_waitcnt lgkmcnt(11)
	v_mfma_f32_16x16x32_bf16 v[110:113], v[194:197], v[238:241], v[110:113]
	v_mfma_f32_16x16x32_bf16 v[106:109], v[194:197], v[242:245], v[106:109]
	v_mfma_f32_16x16x32_bf16 v[102:105], v[194:197], v[246:249], v[102:105]
	v_mfma_f32_16x16x32_bf16 v[98:101], v[194:197], v[222:225], v[98:101]
	s_waitcnt vmcnt(3)
	ds_write_b128 v235, v[34:37] offset:16384
	s_waitcnt vmcnt(2)
	ds_write_b128 v235, v[38:41] offset:18432
	s_waitcnt lgkmcnt(10)
	v_mfma_f32_16x16x32_bf16 v[94:97], v[198:201], v[238:241], v[94:97]
	v_mfma_f32_16x16x32_bf16 v[90:93], v[198:201], v[242:245], v[90:93]
	v_mfma_f32_16x16x32_bf16 v[86:89], v[198:201], v[246:249], v[86:89]
	v_mfma_f32_16x16x32_bf16 v[82:85], v[198:201], v[222:225], v[82:85]
	s_waitcnt vmcnt(1)
	ds_write_b128 v235, v[42:45] offset:20480
	s_waitcnt vmcnt(0)
	ds_write_b128 v235, v[46:49] offset:22528
	s_waitcnt lgkmcnt(9)
	v_mfma_f32_16x16x32_bf16 v[78:81], v[202:205], v[238:241], v[78:81]
	v_mfma_f32_16x16x32_bf16 v[74:77], v[202:205], v[242:245], v[74:77]
	v_mfma_f32_16x16x32_bf16 v[70:73], v[202:205], v[246:249], v[70:73]
	v_mfma_f32_16x16x32_bf16 v[66:69], v[202:205], v[222:225], v[66:69]
	s_waitcnt lgkmcnt(6)
	v_mfma_f32_16x16x32_bf16 v[62:65], v[206:209], v[238:241], v[62:65]
	v_mfma_f32_16x16x32_bf16 v[58:61], v[206:209], v[242:245], v[58:61]
	v_mfma_f32_16x16x32_bf16 v[54:57], v[206:209], v[246:249], v[54:57]
	v_mfma_f32_16x16x32_bf16 v[50:53], v[206:209], v[222:225], v[50:53]
	s_waitcnt lgkmcnt(0)
	s_barrier
; template <int MODE>
; __device__ void gemm_tile2(const u16* __restrict__ X, int lda, const u16* __restrict__ W, int ldb, int K,
;                            int m0, int n0, u16* __restrict__ outb, int vbase,
;                            const float* resid, float* outf, unsigned char* smem) {
;     ...
;   for (int kt2 = 0; kt2 < nk; kt2 += 2) {
; #pragma unroll
;     for (int h = 0; h < 2; ++h) {
;       const int kt = kt2 + h;
;       const u16* st = sbase + h * G2STAGE;
;       bf16x8 fw[4], fx[4];
; #pragma unroll
;       for (int j = 0; j < 4; ++j) fw[j] = *(const bf16x8*)(st + 256 * G2S + (ww * 64 + j * 16 + l15) * G2S + fsw);
; #pragma unroll
;       for (int i = 0; i < 4; ++i) fx[i] = *(const bf16x8*)(st + (wx * 128 + i * 16 + l15) * G2S + fsw);
;       __builtin_amdgcn_sched_barrier(0);
;       __builtin_amdgcn_s_setprio(1);
; #pragma unroll
;       for (int i = 0; i < 4; ++i) {
; #pragma unroll
;         for (int j = 0; j < 4; ++j) {
;           if (MODE == 1) acc[i][j] = mfma16(fx[i], fw[j], acc[i][j]);
;           else acc[i][j] = mfma16(fw[j], fx[i], acc[i][j]);
;         }
;       }
;       __builtin_amdgcn_s_setprio(0);
;       __builtin_amdgcn_sched_barrier(0);
; #pragma unroll
;       for (int i = 0; i < 4; ++i) fx[i] = *(const bf16x8*)(st + (wx * 128 + (i + 4) * 16 + l15) * G2S + fsw);
;       __builtin_amdgcn_sched_barrier(0);
;       if (kt + 1 < nk) G2_LSTORE(1 - h, 1 - h);
;       if (kt + 3 < nk) G2_GLOAD(1 - h, kt + 3);
;       __builtin_amdgcn_sched_barrier(0);
;       __builtin_amdgcn_s_setprio(1);
; #pragma unroll
;       for (int i = 0; i < 4; ++i) {
; #pragma unroll
;         for (int j = 0; j < 4; ++j) {
;           if (MODE == 1) acc[i + 4][j] = mfma16(fx[i], fw[j], acc[i + 4][j]);
;           else acc[i + 4][j] = mfma16(fw[j], fx[i], acc[i + 4][j]);
;         }
;       }
;       __builtin_amdgcn_s_setprio(0);
;       __syncthreads();
;     }
;   }
	s_mov_b32 s35, s7
	s_mov_b32 s7, s6
	s_mov_b32 s6, s1
	s_mov_b32 s1, s35
	ds_read_b128 v[178:181], v236 offset:16384
	ds_read_b128 v[182:185], v236 offset:17408
	ds_read_b128 v[186:189], v236 offset:18432
	ds_read_b128 v[190:193], v236 offset:19456
	ds_read_b128 v[194:197], v237
	ds_read_b128 v[198:201], v237 offset:1024
	ds_read_b128 v[202:205], v237 offset:2048
	ds_read_b128 v[206:209], v237 offset:3072
	s_waitcnt lgkmcnt(3)
	v_mfma_f32_16x16x32_bf16 v[174:177], v[194:197], v[178:181], v[174:177]
	v_mfma_f32_16x16x32_bf16 v[170:173], v[194:197], v[182:185], v[170:173]
	v_mfma_f32_16x16x32_bf16 v[166:169], v[194:197], v[186:189], v[166:169]
	v_mfma_f32_16x16x32_bf16 v[162:165], v[194:197], v[190:193], v[162:165]
	ds_read_b128 v[194:197], v237 offset:4096
	ds_read_b128 v[238:241], v233 offset:16384
	s_waitcnt lgkmcnt(4)
	v_mfma_f32_16x16x32_bf16 v[158:161], v[198:201], v[178:181], v[158:161]
	v_mfma_f32_16x16x32_bf16 v[154:157], v[198:201], v[182:185], v[154:157]
	v_mfma_f32_16x16x32_bf16 v[150:153], v[198:201], v[186:189], v[150:153]
	v_mfma_f32_16x16x32_bf16 v[146:149], v[198:201], v[190:193], v[146:149]
	ds_read_b128 v[198:201], v237 offset:5120
	ds_read_b128 v[242:245], v233 offset:17408
	s_waitcnt lgkmcnt(5)
	v_mfma_f32_16x16x32_bf16 v[142:145], v[202:205], v[178:181], v[142:145]
	v_mfma_f32_16x16x32_bf16 v[138:141], v[202:205], v[182:185], v[138:141]
	v_mfma_f32_16x16x32_bf16 v[134:137], v[202:205], v[186:189], v[134:137]
	v_mfma_f32_16x16x32_bf16 v[130:133], v[202:205], v[190:193], v[130:133]
	ds_read_b128 v[202:205], v237 offset:6144
	ds_read_b128 v[246:249], v233 offset:18432
	s_waitcnt lgkmcnt(6)
	v_mfma_f32_16x16x32_bf16 v[126:129], v[206:209], v[178:181], v[126:129]
	v_mfma_f32_16x16x32_bf16 v[122:125], v[206:209], v[182:185], v[122:125]
	v_mfma_f32_16x16x32_bf16 v[118:121], v[206:209], v[186:189], v[118:121]
	v_mfma_f32_16x16x32_bf16 v[114:117], v[206:209], v[190:193], v[114:117]
	ds_read_b128 v[206:209], v237 offset:7168
	ds_read_b128 v[222:225], v233 offset:19456
	s_sub_i32 s35, s7, s1
	v_add_u32_e32 v236, s35, v236
	v_add_u32_e32 v237, s35, v237
	s_waitcnt lgkmcnt(7)
	v_mfma_f32_16x16x32_bf16 v[110:113], v[194:197], v[178:181], v[110:113]
	v_mfma_f32_16x16x32_bf16 v[106:109], v[194:197], v[182:185], v[106:109]
	v_mfma_f32_16x16x32_bf16 v[102:105], v[194:197], v[186:189], v[102:105]
	v_mfma_f32_16x16x32_bf16 v[98:101], v[194:197], v[190:193], v[98:101]
	ds_read_b128 v[194:197], v232
	s_waitcnt lgkmcnt(6)
	v_mfma_f32_16x16x32_bf16 v[94:97], v[198:201], v[178:181], v[94:97]
	v_mfma_f32_16x16x32_bf16 v[90:93], v[198:201], v[182:185], v[90:93]
	v_mfma_f32_16x16x32_bf16 v[86:89], v[198:201], v[186:189], v[86:89]
	v_mfma_f32_16x16x32_bf16 v[82:85], v[198:201], v[190:193], v[82:85]
	ds_read_b128 v[198:201], v232 offset:1024
	s_waitcnt lgkmcnt(5)
	v_mfma_f32_16x16x32_bf16 v[78:81], v[202:205], v[178:181], v[78:81]
	v_mfma_f32_16x16x32_bf16 v[74:77], v[202:205], v[182:185], v[74:77]
	v_mfma_f32_16x16x32_bf16 v[70:73], v[202:205], v[186:189], v[70:73]
	v_mfma_f32_16x16x32_bf16 v[66:69], v[202:205], v[190:193], v[66:69]
	ds_read_b128 v[202:205], v232 offset:2048
	s_waitcnt lgkmcnt(4)
	v_mfma_f32_16x16x32_bf16 v[62:65], v[206:209], v[178:181], v[62:65]
	v_mfma_f32_16x16x32_bf16 v[58:61], v[206:209], v[182:185], v[58:61]
	v_mfma_f32_16x16x32_bf16 v[54:57], v[206:209], v[186:189], v[54:57]
	v_mfma_f32_16x16x32_bf16 v[50:53], v[206:209], v[190:193], v[50:53]
	ds_read_b128 v[206:209], v232 offset:3072
	s_barrier
	s_waitcnt lgkmcnt(3)
	v_mfma_f32_16x16x32_bf16 v[174:177], v[194:197], v[238:241], v[174:177]
	v_mfma_f32_16x16x32_bf16 v[170:173], v[194:197], v[242:245], v[170:173]
	v_mfma_f32_16x16x32_bf16 v[166:169], v[194:197], v[246:249], v[166:169]
	v_mfma_f32_16x16x32_bf16 v[162:165], v[194:197], v[222:225], v[162:165]
	ds_read_b128 v[194:197], v232 offset:4096
	s_waitcnt lgkmcnt(3)
	v_mfma_f32_16x16x32_bf16 v[158:161], v[198:201], v[238:241], v[158:161]
	v_mfma_f32_16x16x32_bf16 v[154:157], v[198:201], v[242:245], v[154:157]
	v_mfma_f32_16x16x32_bf16 v[150:153], v[198:201], v[246:249], v[150:153]
	v_mfma_f32_16x16x32_bf16 v[146:149], v[198:201], v[222:225], v[146:149]
	ds_read_b128 v[198:201], v232 offset:5120
	s_waitcnt lgkmcnt(3)
	v_mfma_f32_16x16x32_bf16 v[142:145], v[202:205], v[238:241], v[142:145]
	v_mfma_f32_16x16x32_bf16 v[138:141], v[202:205], v[242:245], v[138:141]
	v_mfma_f32_16x16x32_bf16 v[134:137], v[202:205], v[246:249], v[134:137]
	v_mfma_f32_16x16x32_bf16 v[130:133], v[202:205], v[222:225], v[130:133]
	ds_read_b128 v[202:205], v232 offset:6144
	s_waitcnt lgkmcnt(3)
	v_mfma_f32_16x16x32_bf16 v[126:129], v[206:209], v[238:241], v[126:129]
	v_mfma_f32_16x16x32_bf16 v[122:125], v[206:209], v[242:245], v[122:125]
	v_mfma_f32_16x16x32_bf16 v[118:121], v[206:209], v[246:249], v[118:121]
	v_mfma_f32_16x16x32_bf16 v[114:117], v[206:209], v[222:225], v[114:117]
	ds_read_b128 v[206:209], v232 offset:7168
	s_sub_i32 s35, s1, s6
	v_add_u32_e32 v233, s35, v233
	v_add_u32_e32 v232, s35, v232
	s_waitcnt lgkmcnt(3)
	v_mfma_f32_16x16x32_bf16 v[110:113], v[194:197], v[238:241], v[110:113]
	v_mfma_f32_16x16x32_bf16 v[106:109], v[194:197], v[242:245], v[106:109]
	v_mfma_f32_16x16x32_bf16 v[102:105], v[194:197], v[246:249], v[102:105]
	v_mfma_f32_16x16x32_bf16 v[98:101], v[194:197], v[222:225], v[98:101]
	s_waitcnt lgkmcnt(2)
	v_mfma_f32_16x16x32_bf16 v[94:97], v[198:201], v[238:241], v[94:97]
	v_mfma_f32_16x16x32_bf16 v[90:93], v[198:201], v[242:245], v[90:93]
	v_mfma_f32_16x16x32_bf16 v[86:89], v[198:201], v[246:249], v[86:89]
	v_mfma_f32_16x16x32_bf16 v[82:85], v[198:201], v[222:225], v[82:85]
	s_waitcnt lgkmcnt(1)
	v_mfma_f32_16x16x32_bf16 v[78:81], v[202:205], v[238:241], v[78:81]
	v_mfma_f32_16x16x32_bf16 v[74:77], v[202:205], v[242:245], v[74:77]
	v_mfma_f32_16x16x32_bf16 v[70:73], v[202:205], v[246:249], v[70:73]
	v_mfma_f32_16x16x32_bf16 v[66:69], v[202:205], v[222:225], v[66:69]
	s_waitcnt lgkmcnt(0)
	v_mfma_f32_16x16x32_bf16 v[62:65], v[206:209], v[238:241], v[62:65]
	v_mfma_f32_16x16x32_bf16 v[58:61], v[206:209], v[242:245], v[58:61]
	v_mfma_f32_16x16x32_bf16 v[54:57], v[206:209], v[246:249], v[54:57]
	v_mfma_f32_16x16x32_bf16 v[50:53], v[206:209], v[222:225], v[50:53]
	s_barrier
	s_mov_b32 s35, s7
	s_mov_b32 s7, s6
	s_mov_b32 s6, s1
	s_mov_b32 s1, s35
	s_nop 7
	v_and_b32_e32 v232, 15, v0
	s_branch .LBB0_285

; __device__ __forceinline__ int otid() { int t = threadIdx.x; asm volatile("" : "+v"(t)); return t; }
; template <int MODE>
; __device__ void gemm_tile2(const u16* __restrict__ X, int lda, const u16* __restrict__ W, int ldb, int K,
;                            int m0, int n0, u16* __restrict__ outb, int vbase,
;                            const float* resid, float* outf, unsigned char* smem) {
;     ...
;   const int tid = otid(), lane = tid & 63, l15 = lane & 15, quad = lane >> 4;
;   const int wave = tid >> 6;
;   const int wx = wave >> 1, ww = wave & 1;
;   f32x4 acc[8][4];
; #pragma unroll
;   for (int i = 0; i < 8; ++i)
; #pragma unroll
;     for (int j = 0; j < 4; ++j) acc[i][j] = f32x4{0.f, 0.f, 0.f, 0.f};
;   u32x4 rx[2][4], rw[2][2];
;   const int lrow = tid >> 2, lkc = (tid & 3) * 8;
;   const int lsw = ((tid & 3) ^ ((0 - (lrow >> 2)) & 3)) * 8;
;   const int fsw = (quad ^ ((0 - (l15 >> 2)) & 3)) * 8;
;   const auto rsX = __builtin_amdgcn_make_buffer_rsrc((void*)(X + (size_t)m0 * lda), (short)0, 0x7fffffff, 0x00020000);
;   const auto rsW = __builtin_amdgcn_make_buffer_rsrc((void*)(W + (size_t)n0 * ldb), (short)0, 0x7fffffff, 0x00020000);
;   const int vox = (lrow * lda + lkc) * 2, vow = (lrow * ldb + lkc) * 2;
;   const int nk = K / 32;
;     ...
;   G2_GLOAD(0, 0);
;   G2_GLOAD(1, 1);
;   __syncthreads();
;   G2_LSTORE(0, 0);
;   G2_GLOAD(0, 2);
;   __syncthreads();
; __device__ void phase_outproj(const Params& p, int layer, unsigned char* smem) {
;     ...
;   const int xcd = blockIdx.x & 7, loc = blockIdx.x >> 3, nloc = gridDim.x >> 3;
;   for (int idx = loc; idx < 8 * 8; idx += nloc) {
;     int nt = idx >> 3, mt = xcd * 8 + (idx & 7);
;     gemm_tile2<2>(P_XN, DM, W, DM, DM, mt * 256, nt * 128, nullptr, 0, resid, p.out, smem);
.LBB0_337:
	s_and_b32 s6, s18, 7
	v_readlane_b32 s7, v254, 16
	s_or_b32 s29, s6, s7
	s_lshl_b32 s6, s18, 4
	s_and_b32 s19, s6, 0x380
	s_lshl_b32 s7, s29, 19
	s_add_u32 s24, s36, s7
	v_mov_b32_e32 v230, v210
	s_addc_u32 s7, s37, 0
	s_and_b32 s25, s7, 0xffff
	s_lshl_b32 s7, s19, 11
	s_add_u32 s40, s8, s7
	s_addc_u32 s7, s9, 0
	s_and_b32 s41, s7, 0xffff
	s_mov_b32 s42, s26
	s_mov_b32 s43, s27
	v_lshrrev_b32_e32 v0, 4, v230
	v_and_b32_e32 v231, 15, v230
	v_bfe_u32 v233, v230, 6, 1
	v_lshrrev_b32_e32 v2, 2, v230
	v_sub_u32_e32 v2, 0, v2
	v_lshrrev_b32_e32 v3, 4, v230
	v_xor_b32_e32 v2, v3, v2
	v_lshlrev_b32_e32 v2, 4, v2
	v_and_b32_e32 v2, 48, v2
	v_lshlrev_b32_e32 v4, 6, v230
	v_and_b32_e32 v5, 0x3c0, v4
	v_bfe_u32 v6, v230, 6, 1
	v_lshl_or_b32 v6, v6, 12, v2
	v_add_u32_e32 v235, v6, v5
	v_and_b32_e32 v4, 0xffffe3c0, v4
	v_add_u32_e32 v236, v2, v4
	v_xor_b32_e32 v232, 64, v235
	v_add_u32_e32 v232, 0x6000, v232
	v_xor_b32_e32 v237, 64, v236
	v_add_u32_e32 v237, 0x6000, v237
	v_and_b32_e32 v2, 3, v230
	v_bfe_u32 v221, v230, 2, 1
	v_lshrrev_b32_e32 v4, 3, v230
	v_lshrrev_b32_e32 v5, 2, v4
	v_sub_u32_e32 v5, 0, v5
	v_and_b32_e32 v5, 3, v5
	v_xor_b32_e32 v5, v2, v5
	v_lshlrev_b32_e32 v5, 4, v5
	v_lshl_or_b32 v5, v221, 6, v5
	v_lshl_or_b32 v218, v4, 11, v5
	v_add_u32_e32 v219, 0x10000, v218
	v_lshlrev_b32_e32 v2, 4, v2
	v_xor_b32_e32 v4, v4, v221
	v_lshl_or_b32 v220, v4, 6, v2
	buffer_load_dwordx4 v[130:133], v218, s[24:27], 0 offen
	buffer_load_dwordx4 v[134:137], v219, s[24:27], 0 offen
	buffer_load_dwordx4 v[138:141], v218, s[24:27], s27 offen
	buffer_load_dwordx4 v[142:145], v219, s[24:27], s27 offen
	buffer_load_dwordx4 v[146:149], v218, s[24:27], s77 offen
	buffer_load_dwordx4 v[150:153], v219, s[24:27], s77 offen
	buffer_load_dwordx4 v[154:157], v218, s[24:27], s78 offen
	buffer_load_dwordx4 v[158:161], v219, s[24:27], s78 offen
	buffer_load_dwordx4 v[162:165], v218, s[40:43], 0 offen
	buffer_load_dwordx4 v[166:169], v219, s[40:43], 0 offen
	buffer_load_dwordx4 v[170:173], v218, s[40:43], s27 offen
	buffer_load_dwordx4 v[174:177], v219, s[40:43], s27 offen
	v_add_u32_e32 v218, 0x80, v218
	v_add_u32_e32 v219, 0x80, v219
	v_mov_b32_e32 v2, 0
	v_mov_b32_e32 v3, 0
	v_mov_b32_e32 v4, 0
	v_mov_b32_e32 v5, 0
	v_mov_b32_e32 v6, 0
	v_mov_b32_e32 v7, 0
	v_mov_b32_e32 v8, 0
	v_mov_b32_e32 v9, 0
	v_mov_b32_e32 v10, 0
	v_mov_b32_e32 v11, 0
	v_mov_b32_e32 v12, 0
	v_mov_b32_e32 v13, 0
	v_mov_b32_e32 v14, 0
	v_mov_b32_e32 v15, 0
	v_mov_b32_e32 v16, 0
	v_mov_b32_e32 v17, 0
	v_mov_b32_e32 v18, 0
	v_mov_b32_e32 v19, 0
	v_mov_b32_e32 v20, 0
	v_mov_b32_e32 v21, 0
	v_mov_b32_e32 v22, 0
	v_mov_b32_e32 v23, 0
	v_mov_b32_e32 v24, 0
	v_mov_b32_e32 v25, 0
	v_mov_b32_e32 v26, 0
	v_mov_b32_e32 v27, 0
	v_mov_b32_e32 v28, 0
	v_mov_b32_e32 v29, 0
	v_mov_b32_e32 v30, 0
	v_mov_b32_e32 v31, 0
	v_mov_b32_e32 v32, 0
	v_mov_b32_e32 v33, 0
	v_mov_b32_e32 v34, 0
	v_mov_b32_e32 v35, 0
	v_mov_b32_e32 v36, 0
	v_mov_b32_e32 v37, 0
	v_mov_b32_e32 v38, 0
	v_mov_b32_e32 v39, 0
	v_mov_b32_e32 v40, 0
	v_mov_b32_e32 v41, 0
	v_mov_b32_e32 v42, 0
	v_mov_b32_e32 v43, 0
	v_mov_b32_e32 v44, 0
	v_mov_b32_e32 v45, 0
	v_mov_b32_e32 v46, 0
	v_mov_b32_e32 v47, 0
	v_mov_b32_e32 v48, 0
	v_mov_b32_e32 v49, 0
	v_mov_b32_e32 v50, 0
	v_mov_b32_e32 v51, 0
	v_mov_b32_e32 v52, 0
	v_mov_b32_e32 v53, 0
	v_mov_b32_e32 v54, 0
	v_mov_b32_e32 v55, 0
	v_mov_b32_e32 v56, 0
	v_mov_b32_e32 v57, 0
	v_mov_b32_e32 v58, 0
	v_mov_b32_e32 v59, 0
	v_mov_b32_e32 v60, 0
	v_mov_b32_e32 v61, 0
	v_mov_b32_e32 v62, 0
	v_mov_b32_e32 v63, 0
	v_mov_b32_e32 v64, 0
	v_mov_b32_e32 v65, 0
	v_mov_b32_e32 v66, 0
	v_mov_b32_e32 v67, 0
	v_mov_b32_e32 v68, 0
	v_mov_b32_e32 v69, 0
	v_mov_b32_e32 v70, 0
	v_mov_b32_e32 v71, 0
	v_mov_b32_e32 v72, 0
	v_mov_b32_e32 v73, 0
	v_mov_b32_e32 v74, 0
	v_mov_b32_e32 v75, 0
	v_mov_b32_e32 v76, 0
	v_mov_b32_e32 v77, 0
	v_mov_b32_e32 v78, 0
	v_mov_b32_e32 v79, 0
	v_mov_b32_e32 v80, 0
	v_mov_b32_e32 v81, 0
	v_mov_b32_e32 v82, 0
	v_mov_b32_e32 v83, 0
	v_mov_b32_e32 v84, 0
	v_mov_b32_e32 v85, 0
	v_mov_b32_e32 v86, 0
	v_mov_b32_e32 v87, 0
	v_mov_b32_e32 v88, 0
	v_mov_b32_e32 v89, 0
	v_mov_b32_e32 v90, 0
	v_mov_b32_e32 v91, 0
	v_mov_b32_e32 v92, 0
	v_mov_b32_e32 v93, 0
	v_mov_b32_e32 v94, 0
	v_mov_b32_e32 v95, 0
	v_mov_b32_e32 v96, 0
	v_mov_b32_e32 v97, 0
	v_mov_b32_e32 v98, 0
	v_mov_b32_e32 v99, 0
	v_mov_b32_e32 v100, 0
	v_mov_b32_e32 v101, 0
	v_mov_b32_e32 v102, 0
	v_mov_b32_e32 v103, 0
	v_mov_b32_e32 v104, 0
	v_mov_b32_e32 v105, 0
	v_mov_b32_e32 v106, 0
	v_mov_b32_e32 v107, 0
	v_mov_b32_e32 v108, 0
	v_mov_b32_e32 v109, 0
	v_mov_b32_e32 v110, 0
	v_mov_b32_e32 v111, 0
	v_mov_b32_e32 v112, 0
	v_mov_b32_e32 v113, 0
	v_mov_b32_e32 v114, 0
	v_mov_b32_e32 v115, 0
	v_mov_b32_e32 v116, 0
	v_mov_b32_e32 v117, 0
	v_mov_b32_e32 v118, 0
	v_mov_b32_e32 v119, 0
	v_mov_b32_e32 v120, 0
	v_mov_b32_e32 v121, 0
	v_mov_b32_e32 v122, 0
	v_mov_b32_e32 v123, 0
	v_mov_b32_e32 v124, 0
	v_mov_b32_e32 v125, 0
	v_mov_b32_e32 v126, 0
	v_mov_b32_e32 v127, 0
	v_mov_b32_e32 v128, 0
	v_mov_b32_e32 v129, 0
	s_mov_b32 s7, 0
	s_mov_b32 s30, 0x6000
	s_mov_b32 s31, 0xc000
	s_mov_b32 s6, 0
	v_mad_i32_i24 v234, v221, s30, v220
	s_barrier
	s_waitcnt vmcnt(11)
	ds_write_b128 v234, v[130:133]
	s_waitcnt vmcnt(10)
	ds_write_b128 v234, v[134:137] offset:2048
	s_waitcnt vmcnt(9)
	ds_write_b128 v234, v[138:141] offset:4096
	s_waitcnt vmcnt(8)
	ds_write_b128 v234, v[142:145] offset:6144
	s_waitcnt vmcnt(7)
	ds_write_b128 v234, v[146:149] offset:8192
	s_waitcnt vmcnt(6)
	ds_write_b128 v234, v[150:153] offset:10240
	s_waitcnt vmcnt(5)
	ds_write_b128 v234, v[154:157] offset:12288
	s_waitcnt vmcnt(4)
	ds_write_b128 v234, v[158:161] offset:14336
	s_waitcnt vmcnt(3)
	ds_write_b128 v234, v[162:165] offset:16384
	s_waitcnt vmcnt(2)
	ds_write_b128 v234, v[166:169] offset:18432
	s_waitcnt vmcnt(1)
	ds_write_b128 v234, v[170:173] offset:20480
	s_waitcnt vmcnt(0)
	ds_write_b128 v234, v[174:177] offset:22528
	buffer_load_dwordx4 v[130:133], v218, s[24:27], 0 offen
	buffer_load_dwordx4 v[134:137], v219, s[24:27], 0 offen
	buffer_load_dwordx4 v[138:141], v218, s[24:27], s27 offen
	buffer_load_dwordx4 v[142:145], v219, s[24:27], s27 offen
	buffer_load_dwordx4 v[146:149], v218, s[24:27], s77 offen
	buffer_load_dwordx4 v[150:153], v219, s[24:27], s77 offen
	buffer_load_dwordx4 v[154:157], v218, s[24:27], s78 offen
	buffer_load_dwordx4 v[158:161], v219, s[24:27], s78 offen
	buffer_load_dwordx4 v[162:165], v218, s[40:43], 0 offen
	buffer_load_dwordx4 v[166:169], v219, s[40:43], 0 offen
	buffer_load_dwordx4 v[170:173], v218, s[40:43], s27 offen
	buffer_load_dwordx4 v[174:177], v219, s[40:43], s27 offen
	v_add_u32_e32 v218, 0x80, v218
	v_add_u32_e32 v219, 0x80, v219
	s_waitcnt lgkmcnt(0)
	s_barrier
	ds_read_b128 v[178:181], v235 offset:16384
	ds_read_b128 v[182:185], v235 offset:17408
	ds_read_b128 v[186:189], v235 offset:18432
	ds_read_b128 v[190:193], v235 offset:19456
	ds_read_b128 v[194:197], v236
	ds_read_b128 v[198:201], v236 offset:1024
	ds_read_b128 v[202:205], v236 offset:2048
	ds_read_b128 v[206:209], v236 offset:3072
; template <int MODE>
; __device__ void gemm_tile2(const u16* __restrict__ X, int lda, const u16* __restrict__ W, int ldb, int K,
;                            int m0, int n0, u16* __restrict__ outb, int vbase,
;                            const float* resid, float* outf, unsigned char* smem) {
;     ...
;   G2_GLOAD(0, 0);
;   G2_GLOAD(1, 1);
;   __syncthreads();
;   G2_LSTORE(0, 0);
;   G2_GLOAD(0, 2);
;   __syncthreads();
;   for (int kt2 = 0; kt2 < nk; kt2 += 2) {
; #pragma unroll
;     for (int h = 0; h < 2; ++h) {
;       const int kt = kt2 + h;
;       const u16* st = sbase + h * G2STAGE;
;       bf16x8 fw[4], fx[4];
; #pragma unroll
;       for (int j = 0; j < 4; ++j) fw[j] = *(const bf16x8*)(st + 256 * G2S + (ww * 64 + j * 16 + l15) * G2S + fsw);
; #pragma unroll
;       for (int i = 0; i < 4; ++i) fx[i] = *(const bf16x8*)(st + (wx * 128 + i * 16 + l15) * G2S + fsw);
;       __builtin_amdgcn_sched_barrier(0);
;       __builtin_amdgcn_s_setprio(1);
; #pragma unroll
;       for (int i = 0; i < 4; ++i) {
; #pragma unroll
;         for (int j = 0; j < 4; ++j) {
;           if (MODE == 1) acc[i][j] = mfma16(fx[i], fw[j], acc[i][j]);
;           else acc[i][j] = mfma16(fw[j], fx[i], acc[i][j]);
;         }
;       }
;       __builtin_amdgcn_s_setprio(0);
;       __builtin_amdgcn_sched_barrier(0);
; #pragma unroll
;       for (int i = 0; i < 4; ++i) fx[i] = *(const bf16x8*)(st + (wx * 128 + (i + 4) * 16 + l15) * G2S + fsw);
;       __builtin_amdgcn_sched_barrier(0);
;       if (kt + 1 < nk) G2_LSTORE(1 - h, 1 - h);
;       if (kt + 3 < nk) G2_GLOAD(1 - h, kt + 3);
;       __builtin_amdgcn_sched_barrier(0);
;       __builtin_amdgcn_s_setprio(1);
; #pragma unroll
;       for (int i = 0; i < 4; ++i) {
; #pragma unroll
;         for (int j = 0; j < 4; ++j) {
;           if (MODE == 1) acc[i + 4][j] = mfma16(fx[i], fw[j], acc[i + 4][j]);
;           else acc[i + 4][j] = mfma16(fw[j], fx[i], acc[i + 4][j]);
;         }
;       }
;       __builtin_amdgcn_s_setprio(0);
;       __syncthreads();
;     }
.Lf2_loop:
	s_waitcnt lgkmcnt(3)
	v_mfma_f32_16x16x32_bf16 v[126:129], v[178:181], v[194:197], v[126:129]
	v_mfma_f32_16x16x32_bf16 v[122:125], v[182:185], v[194:197], v[122:125]
	v_mfma_f32_16x16x32_bf16 v[118:121], v[186:189], v[194:197], v[118:121]
	v_mfma_f32_16x16x32_bf16 v[114:117], v[190:193], v[194:197], v[114:117]
	ds_read_b128 v[194:197], v236 offset:4096
	ds_read_b128 v[238:241], v232 offset:16384
	s_waitcnt lgkmcnt(4)
	v_mfma_f32_16x16x32_bf16 v[110:113], v[178:181], v[198:201], v[110:113]
	v_mfma_f32_16x16x32_bf16 v[106:109], v[182:185], v[198:201], v[106:109]
	v_mfma_f32_16x16x32_bf16 v[102:105], v[186:189], v[198:201], v[102:105]
	v_mfma_f32_16x16x32_bf16 v[98:101], v[190:193], v[198:201], v[98:101]
	ds_read_b128 v[198:201], v236 offset:5120
	ds_read_b128 v[242:245], v232 offset:17408
	s_waitcnt lgkmcnt(5)
	v_mfma_f32_16x16x32_bf16 v[94:97], v[178:181], v[202:205], v[94:97]
	v_mfma_f32_16x16x32_bf16 v[90:93], v[182:185], v[202:205], v[90:93]
	v_mfma_f32_16x16x32_bf16 v[86:89], v[186:189], v[202:205], v[86:89]
	v_mfma_f32_16x16x32_bf16 v[82:85], v[190:193], v[202:205], v[82:85]
	ds_read_b128 v[202:205], v236 offset:6144
	ds_read_b128 v[246:249], v232 offset:18432
	s_waitcnt lgkmcnt(6)
	v_mfma_f32_16x16x32_bf16 v[78:81], v[178:181], v[206:209], v[78:81]
	v_mfma_f32_16x16x32_bf16 v[74:77], v[182:185], v[206:209], v[74:77]
	v_mfma_f32_16x16x32_bf16 v[70:73], v[186:189], v[206:209], v[70:73]
	v_mfma_f32_16x16x32_bf16 v[66:69], v[190:193], v[206:209], v[66:69]
	ds_read_b128 v[206:209], v236 offset:7168
	ds_read_b128 v[222:225], v232 offset:19456
	s_sub_i32 s35, s31, s7
	v_add_u32_e32 v235, s35, v235
	v_add_u32_e32 v236, s35, v236
	s_waitcnt lgkmcnt(7)
	v_mfma_f32_16x16x32_bf16 v[62:65], v[178:181], v[194:197], v[62:65]
	v_mfma_f32_16x16x32_bf16 v[58:61], v[182:185], v[194:197], v[58:61]
	v_mfma_f32_16x16x32_bf16 v[54:57], v[186:189], v[194:197], v[54:57]
	v_mfma_f32_16x16x32_bf16 v[50:53], v[190:193], v[194:197], v[50:53]
	ds_read_b128 v[194:197], v237
	s_waitcnt lgkmcnt(6)
	v_mfma_f32_16x16x32_bf16 v[46:49], v[178:181], v[198:201], v[46:49]
	v_mfma_f32_16x16x32_bf16 v[42:45], v[182:185], v[198:201], v[42:45]
	v_mfma_f32_16x16x32_bf16 v[38:41], v[186:189], v[198:201], v[38:41]
	v_mfma_f32_16x16x32_bf16 v[34:37], v[190:193], v[198:201], v[34:37]
	ds_read_b128 v[198:201], v237 offset:1024
	s_waitcnt lgkmcnt(5)
	v_mfma_f32_16x16x32_bf16 v[30:33], v[178:181], v[202:205], v[30:33]
	v_mfma_f32_16x16x32_bf16 v[26:29], v[182:185], v[202:205], v[26:29]
	v_mfma_f32_16x16x32_bf16 v[22:25], v[186:189], v[202:205], v[22:25]
	v_mfma_f32_16x16x32_bf16 v[18:21], v[190:193], v[202:205], v[18:21]
	ds_read_b128 v[202:205], v237 offset:2048
	s_waitcnt lgkmcnt(4)
	v_mfma_f32_16x16x32_bf16 v[14:17], v[178:181], v[206:209], v[14:17]
	v_mfma_f32_16x16x32_bf16 v[10:13], v[182:185], v[206:209], v[10:13]
	v_mfma_f32_16x16x32_bf16 v[6:9], v[186:189], v[206:209], v[6:9]
	v_mfma_f32_16x16x32_bf16 v[2:5], v[190:193], v[206:209], v[2:5]
	ds_read_b128 v[206:209], v237 offset:3072
	s_sub_i32 s35, s7, s31
	v_mad_i32_i24 v234, v221, s35, v220
	v_add_u32_e32 v234, s31, v234
	s_barrier
	s_waitcnt lgkmcnt(3)
	v_mfma_f32_16x16x32_bf16 v[126:129], v[238:241], v[194:197], v[126:129]
	v_mfma_f32_16x16x32_bf16 v[122:125], v[242:245], v[194:197], v[122:125]
	v_mfma_f32_16x16x32_bf16 v[118:121], v[246:249], v[194:197], v[118:121]
	v_mfma_f32_16x16x32_bf16 v[114:117], v[222:225], v[194:197], v[114:117]
	ds_read_b128 v[194:197], v237 offset:4096
	s_waitcnt vmcnt(11)
	ds_write_b128 v234, v[130:133]
	s_waitcnt vmcnt(10)
	ds_write_b128 v234, v[134:137] offset:2048
	buffer_load_dwordx4 v[130:133], v218, s[24:27], 0 offen
	buffer_load_dwordx4 v[134:137], v219, s[24:27], 0 offen
	s_waitcnt lgkmcnt(5)
	v_mfma_f32_16x16x32_bf16 v[110:113], v[238:241], v[198:201], v[110:113]
	v_mfma_f32_16x16x32_bf16 v[106:109], v[242:245], v[198:201], v[106:109]
	v_mfma_f32_16x16x32_bf16 v[102:105], v[246:249], v[198:201], v[102:105]
	v_mfma_f32_16x16x32_bf16 v[98:101], v[222:225], v[198:201], v[98:101]
	ds_read_b128 v[198:201], v237 offset:5120
	s_waitcnt vmcnt(11)
	ds_write_b128 v234, v[138:141] offset:4096
	s_waitcnt vmcnt(10)
	ds_write_b128 v234, v[142:145] offset:6144
	buffer_load_dwordx4 v[138:141], v218, s[24:27], s27 offen
	buffer_load_dwordx4 v[142:145], v219, s[24:27], s27 offen
	s_waitcnt lgkmcnt(7)
	v_mfma_f32_16x16x32_bf16 v[94:97], v[238:241], v[202:205], v[94:97]
	v_mfma_f32_16x16x32_bf16 v[90:93], v[242:245], v[202:205], v[90:93]
	v_mfma_f32_16x16x32_bf16 v[86:89], v[246:249], v[202:205], v[86:89]
	v_mfma_f32_16x16x32_bf16 v[82:85], v[222:225], v[202:205], v[82:85]
	ds_read_b128 v[202:205], v237 offset:6144
	s_waitcnt vmcnt(11)
	ds_write_b128 v234, v[146:149] offset:8192
	s_waitcnt vmcnt(10)
	ds_write_b128 v234, v[150:153] offset:10240
	buffer_load_dwordx4 v[146:149], v218, s[24:27], s77 offen
	buffer_load_dwordx4 v[150:153], v219, s[24:27], s77 offen
	s_waitcnt lgkmcnt(9)
	v_mfma_f32_16x16x32_bf16 v[78:81], v[238:241], v[206:209], v[78:81]
	v_mfma_f32_16x16x32_bf16 v[74:77], v[242:245], v[206:209], v[74:77]
	v_mfma_f32_16x16x32_bf16 v[70:73], v[246:249], v[206:209], v[70:73]
	v_mfma_f32_16x16x32_bf16 v[66:69], v[222:225], v[206:209], v[66:69]
	ds_read_b128 v[206:209], v237 offset:7168
	s_sub_i32 s35, s7, s30
	v_add_u32_e32 v232, s35, v232
	v_add_u32_e32 v237, s35, v237
	s_waitcnt vmcnt(11)
	ds_write_b128 v234, v[154:157] offset:12288
	s_waitcnt vmcnt(10)
	ds_write_b128 v234, v[158:161] offset:14336
	buffer_load_dwordx4 v[154:157], v218, s[24:27], s78 offen
	buffer_load_dwordx4 v[158:161], v219, s[24:27], s78 offen
	s_waitcnt lgkmcnt(11)
; template <int MODE>
; __device__ void gemm_tile2(const u16* __restrict__ X, int lda, const u16* __restrict__ W, int ldb, int K,
;                            int m0, int n0, u16* __restrict__ outb, int vbase,
;                            const float* resid, float* outf, unsigned char* smem) {
;     ...
;   G2_GLOAD(0, 0);
;   G2_GLOAD(1, 1);
;   __syncthreads();
;   G2_LSTORE(0, 0);
;   G2_GLOAD(0, 2);
;   __syncthreads();
;   for (int kt2 = 0; kt2 < nk; kt2 += 2) {
; #pragma unroll
;     for (int h = 0; h < 2; ++h) {
;       const int kt = kt2 + h;
;       const u16* st = sbase + h * G2STAGE;
;       bf16x8 fw[4], fx[4];
; #pragma unroll
;       for (int j = 0; j < 4; ++j) fw[j] = *(const bf16x8*)(st + 256 * G2S + (ww * 64 + j * 16 + l15) * G2S + fsw);
; #pragma unroll
;       for (int i = 0; i < 4; ++i) fx[i] = *(const bf16x8*)(st + (wx * 128 + i * 16 + l15) * G2S + fsw);
;       __builtin_amdgcn_sched_barrier(0);
;       __builtin_amdgcn_s_setprio(1);
; #pragma unroll
;       for (int i = 0; i < 4; ++i) {
; #pragma unroll
;         for (int j = 0; j < 4; ++j) {
;           if (MODE == 1) acc[i][j] = mfma16(fx[i], fw[j], acc[i][j]);
;           else acc[i][j] = mfma16(fw[j], fx[i], acc[i][j]);
;         }
;       }
;       __builtin_amdgcn_s_setprio(0);
;       __builtin_amdgcn_sched_barrier(0);
; #pragma unroll
;       for (int i = 0; i < 4; ++i) fx[i] = *(const bf16x8*)(st + (wx * 128 + (i + 4) * 16 + l15) * G2S + fsw);
;       __builtin_amdgcn_sched_barrier(0);
;       if (kt + 1 < nk) G2_LSTORE(1 - h, 1 - h);
;       if (kt + 3 < nk) G2_GLOAD(1 - h, kt + 3);
;       __builtin_amdgcn_sched_barrier(0);
;       __builtin_amdgcn_s_setprio(1);
; #pragma unroll
;       for (int i = 0; i < 4; ++i) {
; #pragma unroll
;         for (int j = 0; j < 4; ++j) {
;           if (MODE == 1) acc[i + 4][j] = mfma16(fx[i], fw[j], acc[i + 4][j]);
;           else acc[i + 4][j] = mfma16(fw[j], fx[i], acc[i + 4][j]);
;         }
;       }
;       __builtin_amdgcn_s_setprio(0);
;       __syncthreads();
;     }
	v_mfma_f32_16x16x32_bf16 v[62:65], v[238:241], v[194:197], v[62:65]
	v_mfma_f32_16x16x32_bf16 v[58:61], v[242:245], v[194:197], v[58:61]
	v_mfma_f32_16x16x32_bf16 v[54:57], v[246:249], v[194:197], v[54:57]
	v_mfma_f32_16x16x32_bf16 v[50:53], v[222:225], v[194:197], v[50:53]
	s_waitcnt vmcnt(11)
	ds_write_b128 v234, v[162:165] offset:16384
	s_waitcnt vmcnt(10)
	ds_write_b128 v234, v[166:169] offset:18432
	buffer_load_dwordx4 v[162:165], v218, s[40:43], 0 offen
	buffer_load_dwordx4 v[166:169], v219, s[40:43], 0 offen
	s_waitcnt lgkmcnt(10)
	v_mfma_f32_16x16x32_bf16 v[46:49], v[238:241], v[198:201], v[46:49]
	v_mfma_f32_16x16x32_bf16 v[42:45], v[242:245], v[198:201], v[42:45]
	v_mfma_f32_16x16x32_bf16 v[38:41], v[246:249], v[198:201], v[38:41]
	v_mfma_f32_16x16x32_bf16 v[34:37], v[222:225], v[198:201], v[34:37]
	s_waitcnt vmcnt(11)
	ds_write_b128 v234, v[170:173] offset:20480
	s_waitcnt vmcnt(10)
	ds_write_b128 v234, v[174:177] offset:22528
	buffer_load_dwordx4 v[170:173], v218, s[40:43], s27 offen
	buffer_load_dwordx4 v[174:177], v219, s[40:43], s27 offen
	s_waitcnt lgkmcnt(9)
	v_mfma_f32_16x16x32_bf16 v[30:33], v[238:241], v[202:205], v[30:33]
	v_mfma_f32_16x16x32_bf16 v[26:29], v[242:245], v[202:205], v[26:29]
	v_mfma_f32_16x16x32_bf16 v[22:25], v[246:249], v[202:205], v[22:25]
	v_mfma_f32_16x16x32_bf16 v[18:21], v[222:225], v[202:205], v[18:21]
	s_waitcnt lgkmcnt(6)
	v_mfma_f32_16x16x32_bf16 v[14:17], v[238:241], v[206:209], v[14:17]
	v_mfma_f32_16x16x32_bf16 v[10:13], v[242:245], v[206:209], v[10:13]
	v_mfma_f32_16x16x32_bf16 v[6:9], v[246:249], v[206:209], v[6:9]
	v_mfma_f32_16x16x32_bf16 v[2:5], v[222:225], v[206:209], v[2:5]
	v_add_u32_e32 v218, 0x80, v218
	v_add_u32_e32 v219, 0x80, v219
	s_waitcnt lgkmcnt(0)
	s_barrier
	s_mov_b32 s35, s31
	s_mov_b32 s31, s30
	s_mov_b32 s30, s7
	s_mov_b32 s7, s35
	ds_read_b128 v[178:181], v235 offset:16384
	ds_read_b128 v[182:185], v235 offset:17408
	ds_read_b128 v[186:189], v235 offset:18432
	ds_read_b128 v[190:193], v235 offset:19456
	ds_read_b128 v[194:197], v236
	ds_read_b128 v[198:201], v236 offset:1024
	ds_read_b128 v[202:205], v236 offset:2048
	ds_read_b128 v[206:209], v236 offset:3072
	s_add_u32 s6, s6, 1
	s_cmp_lt_u32 s6, 14
	s_cbranch_scc1 .Lf2_loop
	s_waitcnt lgkmcnt(3)
	v_mfma_f32_16x16x32_bf16 v[126:129], v[178:181], v[194:197], v[126:129]
	v_mfma_f32_16x16x32_bf16 v[122:125], v[182:185], v[194:197], v[122:125]
	v_mfma_f32_16x16x32_bf16 v[118:121], v[186:189], v[194:197], v[118:121]
	v_mfma_f32_16x16x32_bf16 v[114:117], v[190:193], v[194:197], v[114:117]
	ds_read_b128 v[194:197], v236 offset:4096
	ds_read_b128 v[238:241], v232 offset:16384
	s_waitcnt lgkmcnt(4)
	v_mfma_f32_16x16x32_bf16 v[110:113], v[178:181], v[198:201], v[110:113]
	v_mfma_f32_16x16x32_bf16 v[106:109], v[182:185], v[198:201], v[106:109]
	v_mfma_f32_16x16x32_bf16 v[102:105], v[186:189], v[198:201], v[102:105]
	v_mfma_f32_16x16x32_bf16 v[98:101], v[190:193], v[198:201], v[98:101]
	ds_read_b128 v[198:201], v236 offset:5120
	ds_read_b128 v[242:245], v232 offset:17408
	s_waitcnt lgkmcnt(5)
	v_mfma_f32_16x16x32_bf16 v[94:97], v[178:181], v[202:205], v[94:97]
	v_mfma_f32_16x16x32_bf16 v[90:93], v[182:185], v[202:205], v[90:93]
	v_mfma_f32_16x16x32_bf16 v[86:89], v[186:189], v[202:205], v[86:89]
	v_mfma_f32_16x16x32_bf16 v[82:85], v[190:193], v[202:205], v[82:85]
	ds_read_b128 v[202:205], v236 offset:6144
	ds_read_b128 v[246:249], v232 offset:18432
	s_waitcnt lgkmcnt(6)
	v_mfma_f32_16x16x32_bf16 v[78:81], v[178:181], v[206:209], v[78:81]
	v_mfma_f32_16x16x32_bf16 v[74:77], v[182:185], v[206:209], v[74:77]
	v_mfma_f32_16x16x32_bf16 v[70:73], v[186:189], v[206:209], v[70:73]
	v_mfma_f32_16x16x32_bf16 v[66:69], v[190:193], v[206:209], v[66:69]
	ds_read_b128 v[206:209], v236 offset:7168
	ds_read_b128 v[222:225], v232 offset:19456
	s_sub_i32 s35, s31, s7
	v_add_u32_e32 v235, s35, v235
	v_add_u32_e32 v236, s35, v236
	s_waitcnt lgkmcnt(7)
	v_mfma_f32_16x16x32_bf16 v[62:65], v[178:181], v[194:197], v[62:65]
	v_mfma_f32_16x16x32_bf16 v[58:61], v[182:185], v[194:197], v[58:61]
	v_mfma_f32_16x16x32_bf16 v[54:57], v[186:189], v[194:197], v[54:57]
	v_mfma_f32_16x16x32_bf16 v[50:53], v[190:193], v[194:197], v[50:53]
	ds_read_b128 v[194:197], v237
	s_waitcnt lgkmcnt(6)
	v_mfma_f32_16x16x32_bf16 v[46:49], v[178:181], v[198:201], v[46:49]
	v_mfma_f32_16x16x32_bf16 v[42:45], v[182:185], v[198:201], v[42:45]
	v_mfma_f32_16x16x32_bf16 v[38:41], v[186:189], v[198:201], v[38:41]
	v_mfma_f32_16x16x32_bf16 v[34:37], v[190:193], v[198:201], v[34:37]
	ds_read_b128 v[198:201], v237 offset:1024
	s_waitcnt lgkmcnt(5)
	v_mfma_f32_16x16x32_bf16 v[30:33], v[178:181], v[202:205], v[30:33]
	v_mfma_f32_16x16x32_bf16 v[26:29], v[182:185], v[202:205], v[26:29]
	v_mfma_f32_16x16x32_bf16 v[22:25], v[186:189], v[202:205], v[22:25]
	v_mfma_f32_16x16x32_bf16 v[18:21], v[190:193], v[202:205], v[18:21]
	ds_read_b128 v[202:205], v237 offset:2048
	s_waitcnt lgkmcnt(4)
	v_mfma_f32_16x16x32_bf16 v[14:17], v[178:181], v[206:209], v[14:17]
	v_mfma_f32_16x16x32_bf16 v[10:13], v[182:185], v[206:209], v[10:13]
	v_mfma_f32_16x16x32_bf16 v[6:9], v[186:189], v[206:209], v[6:9]
	v_mfma_f32_16x16x32_bf16 v[2:5], v[190:193], v[206:209], v[2:5]
	ds_read_b128 v[206:209], v237 offset:3072
	s_sub_i32 s35, s7, s31
	v_mad_i32_i24 v234, v221, s35, v220
	v_add_u32_e32 v234, s31, v234
	s_barrier
; template <int MODE>
; __device__ void gemm_tile2(const u16* __restrict__ X, int lda, const u16* __restrict__ W, int ldb, int K,
;                            int m0, int n0, u16* __restrict__ outb, int vbase,
;                            const float* resid, float* outf, unsigned char* smem) {
;     ...
; #pragma unroll
;       for (int i = 0; i < 4; ++i) fx[i] = *(const bf16x8*)(st + (wx * 128 + (i + 4) * 16 + l15) * G2S + fsw);
;       __builtin_amdgcn_sched_barrier(0);
;       if (kt + 1 < nk) G2_LSTORE(1 - h, 1 - h);
;       if (kt + 3 < nk) G2_GLOAD(1 - h, kt + 3);
;       __builtin_amdgcn_sched_barrier(0);
;       __builtin_amdgcn_s_setprio(1);
; #pragma unroll
;       for (int i = 0; i < 4; ++i) {
; #pragma unroll
;         for (int j = 0; j < 4; ++j) {
;           if (MODE == 1) acc[i + 4][j] = mfma16(fx[i], fw[j], acc[i + 4][j]);
;           else acc[i + 4][j] = mfma16(fw[j], fx[i], acc[i + 4][j]);
;         }
;       }
;       __builtin_amdgcn_s_setprio(0);
;       __syncthreads();
	s_waitcnt lgkmcnt(3)
	v_mfma_f32_16x16x32_bf16 v[126:129], v[238:241], v[194:197], v[126:129]
	v_mfma_f32_16x16x32_bf16 v[122:125], v[242:245], v[194:197], v[122:125]
	v_mfma_f32_16x16x32_bf16 v[118:121], v[246:249], v[194:197], v[118:121]
	v_mfma_f32_16x16x32_bf16 v[114:117], v[222:225], v[194:197], v[114:117]
	ds_read_b128 v[194:197], v237 offset:4096
	s_waitcnt vmcnt(11)
	ds_write_b128 v234, v[130:133]
	s_waitcnt vmcnt(10)
	ds_write_b128 v234, v[134:137] offset:2048
	s_waitcnt lgkmcnt(5)
	v_mfma_f32_16x16x32_bf16 v[110:113], v[238:241], v[198:201], v[110:113]
	v_mfma_f32_16x16x32_bf16 v[106:109], v[242:245], v[198:201], v[106:109]
	v_mfma_f32_16x16x32_bf16 v[102:105], v[246:249], v[198:201], v[102:105]
	v_mfma_f32_16x16x32_bf16 v[98:101], v[222:225], v[198:201], v[98:101]
	ds_read_b128 v[198:201], v237 offset:5120
	s_waitcnt vmcnt(9)
	ds_write_b128 v234, v[138:141] offset:4096
	s_waitcnt vmcnt(8)
	ds_write_b128 v234, v[142:145] offset:6144
	s_waitcnt lgkmcnt(7)
	v_mfma_f32_16x16x32_bf16 v[94:97], v[238:241], v[202:205], v[94:97]
	v_mfma_f32_16x16x32_bf16 v[90:93], v[242:245], v[202:205], v[90:93]
	v_mfma_f32_16x16x32_bf16 v[86:89], v[246:249], v[202:205], v[86:89]
	v_mfma_f32_16x16x32_bf16 v[82:85], v[222:225], v[202:205], v[82:85]
	ds_read_b128 v[202:205], v237 offset:6144
	s_waitcnt vmcnt(7)
	ds_write_b128 v234, v[146:149] offset:8192
	s_waitcnt vmcnt(6)
	ds_write_b128 v234, v[150:153] offset:10240
	s_waitcnt lgkmcnt(9)
	v_mfma_f32_16x16x32_bf16 v[78:81], v[238:241], v[206:209], v[78:81]
	v_mfma_f32_16x16x32_bf16 v[74:77], v[242:245], v[206:209], v[74:77]
	v_mfma_f32_16x16x32_bf16 v[70:73], v[246:249], v[206:209], v[70:73]
	v_mfma_f32_16x16x32_bf16 v[66:69], v[222:225], v[206:209], v[66:69]
	ds_read_b128 v[206:209], v237 offset:7168
	s_sub_i32 s35, s7, s30
	v_add_u32_e32 v232, s35, v232
	v_add_u32_e32 v237, s35, v237
	s_waitcnt vmcnt(5)
	ds_write_b128 v234, v[154:157] offset:12288
	s_waitcnt vmcnt(4)
	ds_write_b128 v234, v[158:161] offset:14336
	s_waitcnt lgkmcnt(11)
	v_mfma_f32_16x16x32_bf16 v[62:65], v[238:241], v[194:197], v[62:65]
	v_mfma_f32_16x16x32_bf16 v[58:61], v[242:245], v[194:197], v[58:61]
	v_mfma_f32_16x16x32_bf16 v[54:57], v[246:249], v[194:197], v[54:57]
	v_mfma_f32_16x16x32_bf16 v[50:53], v[222:225], v[194:197], v[50:53]
	s_waitcnt vmcnt(3)
	ds_write_b128 v234, v[162:165] offset:16384
	s_waitcnt vmcnt(2)
	ds_write_b128 v234, v[166:169] offset:18432
	s_waitcnt lgkmcnt(10)
	v_mfma_f32_16x16x32_bf16 v[46:49], v[238:241], v[198:201], v[46:49]
	v_mfma_f32_16x16x32_bf16 v[42:45], v[242:245], v[198:201], v[42:45]
	v_mfma_f32_16x16x32_bf16 v[38:41], v[246:249], v[198:201], v[38:41]
	v_mfma_f32_16x16x32_bf16 v[34:37], v[222:225], v[198:201], v[34:37]
	s_waitcnt vmcnt(1)
	ds_write_b128 v234, v[170:173] offset:20480
	s_waitcnt vmcnt(0)
	ds_write_b128 v234, v[174:177] offset:22528
	s_waitcnt lgkmcnt(9)
	v_mfma_f32_16x16x32_bf16 v[30:33], v[238:241], v[202:205], v[30:33]
	v_mfma_f32_16x16x32_bf16 v[26:29], v[242:245], v[202:205], v[26:29]
	v_mfma_f32_16x16x32_bf16 v[22:25], v[246:249], v[202:205], v[22:25]
	v_mfma_f32_16x16x32_bf16 v[18:21], v[222:225], v[202:205], v[18:21]
	s_waitcnt lgkmcnt(6)
	v_mfma_f32_16x16x32_bf16 v[14:17], v[238:241], v[206:209], v[14:17]
	v_mfma_f32_16x16x32_bf16 v[10:13], v[242:245], v[206:209], v[10:13]
	v_mfma_f32_16x16x32_bf16 v[6:9], v[246:249], v[206:209], v[6:9]
	v_mfma_f32_16x16x32_bf16 v[2:5], v[222:225], v[206:209], v[2:5]
	s_waitcnt lgkmcnt(0)
	s_barrier
; template <int MODE>
; __device__ void gemm_tile2(const u16* __restrict__ X, int lda, const u16* __restrict__ W, int ldb, int K,
;                            int m0, int n0, u16* __restrict__ outb, int vbase,
;                            const float* resid, float* outf, unsigned char* smem) {
;     ...
;   for (int kt2 = 0; kt2 < nk; kt2 += 2) {
; #pragma unroll
;     for (int h = 0; h < 2; ++h) {
;       const int kt = kt2 + h;
;       const u16* st = sbase + h * G2STAGE;
;       bf16x8 fw[4], fx[4];
; #pragma unroll
;       for (int j = 0; j < 4; ++j) fw[j] = *(const bf16x8*)(st + 256 * G2S + (ww * 64 + j * 16 + l15) * G2S + fsw);
; #pragma unroll
;       for (int i = 0; i < 4; ++i) fx[i] = *(const bf16x8*)(st + (wx * 128 + i * 16 + l15) * G2S + fsw);
;       __builtin_amdgcn_sched_barrier(0);
;       __builtin_amdgcn_s_setprio(1);
; #pragma unroll
;       for (int i = 0; i < 4; ++i) {
; #pragma unroll
;         for (int j = 0; j < 4; ++j) {
;           if (MODE == 1) acc[i][j] = mfma16(fx[i], fw[j], acc[i][j]);
;           else acc[i][j] = mfma16(fw[j], fx[i], acc[i][j]);
;         }
;       }
;       __builtin_amdgcn_s_setprio(0);
;       __builtin_amdgcn_sched_barrier(0);
; #pragma unroll
;       for (int i = 0; i < 4; ++i) fx[i] = *(const bf16x8*)(st + (wx * 128 + (i + 4) * 16 + l15) * G2S + fsw);
;       __builtin_amdgcn_sched_barrier(0);
;       if (kt + 1 < nk) G2_LSTORE(1 - h, 1 - h);
;       if (kt + 3 < nk) G2_GLOAD(1 - h, kt + 3);
;       __builtin_amdgcn_sched_barrier(0);
;       __builtin_amdgcn_s_setprio(1);
; #pragma unroll
;       for (int i = 0; i < 4; ++i) {
; #pragma unroll
;         for (int j = 0; j < 4; ++j) {
;           if (MODE == 1) acc[i + 4][j] = mfma16(fx[i], fw[j], acc[i + 4][j]);
;           else acc[i + 4][j] = mfma16(fw[j], fx[i], acc[i + 4][j]);
;         }
;       }
;       __builtin_amdgcn_s_setprio(0);
;       __syncthreads();
;     }
;   }
	s_mov_b32 s35, s31
	s_mov_b32 s31, s30
	s_mov_b32 s30, s7
	s_mov_b32 s7, s35
	ds_read_b128 v[178:181], v235 offset:16384
	ds_read_b128 v[182:185], v235 offset:17408
	ds_read_b128 v[186:189], v235 offset:18432
	ds_read_b128 v[190:193], v235 offset:19456
	ds_read_b128 v[194:197], v236
	ds_read_b128 v[198:201], v236 offset:1024
	ds_read_b128 v[202:205], v236 offset:2048
	ds_read_b128 v[206:209], v236 offset:3072
	s_waitcnt lgkmcnt(3)
	v_mfma_f32_16x16x32_bf16 v[126:129], v[178:181], v[194:197], v[126:129]
	v_mfma_f32_16x16x32_bf16 v[122:125], v[182:185], v[194:197], v[122:125]
	v_mfma_f32_16x16x32_bf16 v[118:121], v[186:189], v[194:197], v[118:121]
	v_mfma_f32_16x16x32_bf16 v[114:117], v[190:193], v[194:197], v[114:117]
	ds_read_b128 v[194:197], v236 offset:4096
	ds_read_b128 v[238:241], v232 offset:16384
	s_waitcnt lgkmcnt(4)
	v_mfma_f32_16x16x32_bf16 v[110:113], v[178:181], v[198:201], v[110:113]
	v_mfma_f32_16x16x32_bf16 v[106:109], v[182:185], v[198:201], v[106:109]
	v_mfma_f32_16x16x32_bf16 v[102:105], v[186:189], v[198:201], v[102:105]
	v_mfma_f32_16x16x32_bf16 v[98:101], v[190:193], v[198:201], v[98:101]
	ds_read_b128 v[198:201], v236 offset:5120
	ds_read_b128 v[242:245], v232 offset:17408
	s_waitcnt lgkmcnt(5)
	v_mfma_f32_16x16x32_bf16 v[94:97], v[178:181], v[202:205], v[94:97]
	v_mfma_f32_16x16x32_bf16 v[90:93], v[182:185], v[202:205], v[90:93]
	v_mfma_f32_16x16x32_bf16 v[86:89], v[186:189], v[202:205], v[86:89]
	v_mfma_f32_16x16x32_bf16 v[82:85], v[190:193], v[202:205], v[82:85]
	ds_read_b128 v[202:205], v236 offset:6144
	ds_read_b128 v[246:249], v232 offset:18432
	s_waitcnt lgkmcnt(6)
	v_mfma_f32_16x16x32_bf16 v[78:81], v[178:181], v[206:209], v[78:81]
	v_mfma_f32_16x16x32_bf16 v[74:77], v[182:185], v[206:209], v[74:77]
	v_mfma_f32_16x16x32_bf16 v[70:73], v[186:189], v[206:209], v[70:73]
	v_mfma_f32_16x16x32_bf16 v[66:69], v[190:193], v[206:209], v[66:69]
	ds_read_b128 v[206:209], v236 offset:7168
	ds_read_b128 v[222:225], v232 offset:19456
	s_sub_i32 s35, s31, s7
	v_add_u32_e32 v235, s35, v235
	v_add_u32_e32 v236, s35, v236
	s_waitcnt lgkmcnt(7)
	v_mfma_f32_16x16x32_bf16 v[62:65], v[178:181], v[194:197], v[62:65]
	v_mfma_f32_16x16x32_bf16 v[58:61], v[182:185], v[194:197], v[58:61]
	v_mfma_f32_16x16x32_bf16 v[54:57], v[186:189], v[194:197], v[54:57]
	v_mfma_f32_16x16x32_bf16 v[50:53], v[190:193], v[194:197], v[50:53]
	ds_read_b128 v[194:197], v237
	s_waitcnt lgkmcnt(6)
	v_mfma_f32_16x16x32_bf16 v[46:49], v[178:181], v[198:201], v[46:49]
	v_mfma_f32_16x16x32_bf16 v[42:45], v[182:185], v[198:201], v[42:45]
	v_mfma_f32_16x16x32_bf16 v[38:41], v[186:189], v[198:201], v[38:41]
	v_mfma_f32_16x16x32_bf16 v[34:37], v[190:193], v[198:201], v[34:37]
	ds_read_b128 v[198:201], v237 offset:1024
	s_waitcnt lgkmcnt(5)
	v_mfma_f32_16x16x32_bf16 v[30:33], v[178:181], v[202:205], v[30:33]
	v_mfma_f32_16x16x32_bf16 v[26:29], v[182:185], v[202:205], v[26:29]
	v_mfma_f32_16x16x32_bf16 v[22:25], v[186:189], v[202:205], v[22:25]
	v_mfma_f32_16x16x32_bf16 v[18:21], v[190:193], v[202:205], v[18:21]
	ds_read_b128 v[202:205], v237 offset:2048
	s_waitcnt lgkmcnt(4)
	v_mfma_f32_16x16x32_bf16 v[14:17], v[178:181], v[206:209], v[14:17]
	v_mfma_f32_16x16x32_bf16 v[10:13], v[182:185], v[206:209], v[10:13]
	v_mfma_f32_16x16x32_bf16 v[6:9], v[186:189], v[206:209], v[6:9]
	v_mfma_f32_16x16x32_bf16 v[2:5], v[190:193], v[206:209], v[2:5]
	ds_read_b128 v[206:209], v237 offset:3072
	s_barrier
	s_waitcnt lgkmcnt(3)
	v_mfma_f32_16x16x32_bf16 v[126:129], v[238:241], v[194:197], v[126:129]
	v_mfma_f32_16x16x32_bf16 v[122:125], v[242:245], v[194:197], v[122:125]
	v_mfma_f32_16x16x32_bf16 v[118:121], v[246:249], v[194:197], v[118:121]
	v_mfma_f32_16x16x32_bf16 v[114:117], v[222:225], v[194:197], v[114:117]
	ds_read_b128 v[194:197], v237 offset:4096
	s_waitcnt lgkmcnt(3)
	v_mfma_f32_16x16x32_bf16 v[110:113], v[238:241], v[198:201], v[110:113]
	v_mfma_f32_16x16x32_bf16 v[106:109], v[242:245], v[198:201], v[106:109]
	v_mfma_f32_16x16x32_bf16 v[102:105], v[246:249], v[198:201], v[102:105]
	v_mfma_f32_16x16x32_bf16 v[98:101], v[222:225], v[198:201], v[98:101]
	ds_read_b128 v[198:201], v237 offset:5120
	s_waitcnt lgkmcnt(3)
	v_mfma_f32_16x16x32_bf16 v[94:97], v[238:241], v[202:205], v[94:97]
	v_mfma_f32_16x16x32_bf16 v[90:93], v[242:245], v[202:205], v[90:93]
	v_mfma_f32_16x16x32_bf16 v[86:89], v[246:249], v[202:205], v[86:89]
	v_mfma_f32_16x16x32_bf16 v[82:85], v[222:225], v[202:205], v[82:85]
	ds_read_b128 v[202:205], v237 offset:6144
	s_waitcnt lgkmcnt(3)
	v_mfma_f32_16x16x32_bf16 v[78:81], v[238:241], v[206:209], v[78:81]
	v_mfma_f32_16x16x32_bf16 v[74:77], v[242:245], v[206:209], v[74:77]
	v_mfma_f32_16x16x32_bf16 v[70:73], v[246:249], v[206:209], v[70:73]
	v_mfma_f32_16x16x32_bf16 v[66:69], v[222:225], v[206:209], v[66:69]
	ds_read_b128 v[206:209], v237 offset:7168
	s_sub_i32 s35, s7, s30
	v_add_u32_e32 v232, s35, v232
	v_add_u32_e32 v237, s35, v237
	s_waitcnt lgkmcnt(3)
	v_mfma_f32_16x16x32_bf16 v[62:65], v[238:241], v[194:197], v[62:65]
	v_mfma_f32_16x16x32_bf16 v[58:61], v[242:245], v[194:197], v[58:61]
	v_mfma_f32_16x16x32_bf16 v[54:57], v[246:249], v[194:197], v[54:57]
	v_mfma_f32_16x16x32_bf16 v[50:53], v[222:225], v[194:197], v[50:53]
	s_waitcnt lgkmcnt(2)
	v_mfma_f32_16x16x32_bf16 v[46:49], v[238:241], v[198:201], v[46:49]
	v_mfma_f32_16x16x32_bf16 v[42:45], v[242:245], v[198:201], v[42:45]
	v_mfma_f32_16x16x32_bf16 v[38:41], v[246:249], v[198:201], v[38:41]
	v_mfma_f32_16x16x32_bf16 v[34:37], v[222:225], v[198:201], v[34:37]
	s_waitcnt lgkmcnt(1)
	v_mfma_f32_16x16x32_bf16 v[30:33], v[238:241], v[202:205], v[30:33]
	v_mfma_f32_16x16x32_bf16 v[26:29], v[242:245], v[202:205], v[26:29]
	v_mfma_f32_16x16x32_bf16 v[22:25], v[246:249], v[202:205], v[22:25]
	v_mfma_f32_16x16x32_bf16 v[18:21], v[222:225], v[202:205], v[18:21]
	s_waitcnt lgkmcnt(0)
	v_mfma_f32_16x16x32_bf16 v[14:17], v[238:241], v[206:209], v[14:17]
	v_mfma_f32_16x16x32_bf16 v[10:13], v[242:245], v[206:209], v[10:13]
	v_mfma_f32_16x16x32_bf16 v[6:9], v[246:249], v[206:209], v[6:9]
	v_mfma_f32_16x16x32_bf16 v[2:5], v[222:225], v[206:209], v[2:5]
	s_barrier
	s_mov_b32 s35, s31
	s_mov_b32 s31, s30
	s_mov_b32 s30, s7
	s_mov_b32 s7, s35
	s_nop 7
